# plus differential-attention QK^T: K fragments of k-steps 2,3 prefetched at segment start into spare registers
# speedup vs baseline: 1.0015x; 1.0003x over previous
; __device__ __forceinline__ int opaque_tid() { int t = threadIdx.x; asm volatile("" : "+v"(t)); return t; }
; __device__ __forceinline__ int crow(int r, int hi) { return (r & 3) + 8 * (r >> 2) + 4 * hi; }
; template <int DK, bool NA, bool QL, int SD> ...
;     ...
;   if (hi == 0) li_l[r32] = l_reg; asm volatile("s_waitcnt vmcnt(0) lgkmcnt(0)" ::: "memory");
; #pragma unroll
;   for (int r = 0; r < 16; ++r) { const float rl = __builtin_amdgcn_rcpf(li_l[crow(r, hi)]);
; #pragma unroll
;     for (int d = 0; d < 4; ++d) o[d][r] *= rl; }
; __global__ void __launch_bounds__(NTHR) mega_fwd(Params p) {
;     ...
;                     { const int t3 = opaque_tid(), l3 = t3 & 63, r32 = l3 & 31; const v4u* STv = (const v4u*)((char*)lds + 69632) + t3;
;                       const float* sg = p.diff_subln + l * 128;
;                       float gsub[4], ss[16];
; #pragma unroll
;                       for (int d = 0; d < 4; ++d) gsub[d] = sg[32 * d + r32] * (1.0f - lam_init);
; #pragma unroll
;                       for (int r = 0; r < 16; ++r) ss[r] = 0.f;
; #pragma unroll
;                       for (int k = 0; k < 8; ++k) { const int d = k >> 1, r0 = 8 * (k & 1); const v4u w = STv[k * 512];
; #pragma unroll
;                           for (int i = 0; i < 4; ++i) { const unsigned wi = i == 0 ? w.x : (i == 1 ? w.y : (i == 2 ? w.z : w.w));
;                               const float va = bf2f((unsigned short)(wi & 0xffffu)) - lam * o[d][r0 + 2 * i], vb = bf2f((unsigned short)(wi >> 16)) - lam * o[d][r0 + 2 * i + 1];
;                               o[d][r0 + 2 * i] = va; o[d][r0 + 2 * i + 1] = vb; ss[r0 + 2 * i] += va * va; ss[r0 + 2 * i + 1] += vb * vb; } }
.LBB0_368:
	s_or_b64 exec, exec, s[2:3]
	v_mov_b32_e32 v190, 0x260
	v_mov_b32_e32 v191, 1
	v_mbcnt_lo_u32_b32 v192, -1, 0
	v_mbcnt_hi_u32_b32 v192, -1, v192
	v_mov_b32_e32 v193, 0x3a83126f
	v_mov_b64_e32 v[168:169], 0x100
	v_mov_b64_e32 v[170:171], 0xff
	v_mov_b32_e32 v194, 0x3c23d70a
	v_mov_b32_e32 v195, 0x2800
	v_mov_b64_e32 v[196:197], 0x580
	s_waitcnt vmcnt(0) lgkmcnt(0)
	v_add_u32_e32 v0, v207, v0
	ds_read_b128 v[72:75], v0
	ds_read_b128 v[76:79], v0 offset:32
	v_readlane_b32 s0, v255, 40
	v_readlane_b32 s1, v255, 41
	s_mov_b32 s2, 0xf800000
	s_waitcnt lgkmcnt(1)
	v_rcp_f32_e32 v67, v72
	v_rcp_f32_e32 v68, v73
	v_mul_f32_e32 v70, v67, v34
	v_mul_f32_e32 v34, v67, v18
	v_rcp_f32_e32 v18, v74
	v_mul_f32_e32 v69, v67, v50
	v_mul_f32_e32 v71, v68, v35
	v_mul_f32_e32 v66, v68, v19
	v_mul_f32_e32 v50, v18, v4
	v_rcp_f32_e32 v4, v75
	v_mul_f32_e32 v72, v18, v52
	v_mul_f32_e32 v73, v18, v36
	v_mul_f32_e32 v36, v18, v20
	v_mul_f32_e32 v82, v4, v5
	v_mul_f32_e32 v74, v4, v53
	v_mul_f32_e32 v53, v4, v37
	v_mul_f32_e32 v52, v4, v21
	s_waitcnt lgkmcnt(0)
	v_rcp_f32_e32 v4, v76
	v_mul_f32_e32 v2, v67, v2
	v_mul_f32_e32 v3, v68, v3
	v_mul_f32_e32 v51, v68, v51
	v_mul_f32_e32 v37, v4, v6
	v_mul_f32_e32 v80, v4, v54
	v_mul_f32_e32 v76, v4, v38
	v_mul_f32_e32 v75, v4, v22
	v_rcp_f32_e32 v4, v77
	s_nop 0
	v_mul_f32_e32 v54, v4, v7
	v_mul_f32_e32 v38, v4, v55
	v_mul_f32_e32 v81, v4, v39
	v_mul_f32_e32 v77, v4, v23
	v_rcp_f32_e32 v4, v78
	ds_read_b128 v[20:23], v0 offset:64
	v_mul_f32_e32 v55, v4, v8
	v_mul_f32_e32 v88, v4, v56
	v_mul_f32_e32 v84, v4, v40
	v_mul_f32_e32 v40, v4, v24
	v_rcp_f32_e32 v4, v79
	s_nop 0
	v_mul_f32_e32 v86, v4, v9
	v_mul_f32_e32 v57, v4, v57
	v_mul_f32_e32 v85, v4, v41
	v_mul_f32_e32 v41, v4, v25
	s_waitcnt lgkmcnt(0)
	v_rcp_f32_e32 v4, v20
	s_nop 0
	v_mul_f32_e32 v7, v4, v10
	v_mul_f32_e32 v8, v4, v58
	v_mul_f32_e32 v10, v4, v42
	v_mul_f32_e32 v18, v4, v26
	v_rcp_f32_e32 v4, v21
	s_nop 0
	v_mul_f32_e32 v9, v4, v11
	v_mul_f32_e32 v21, v4, v59
	v_mul_f32_e32 v35, v4, v43
	v_mul_f32_e32 v20, v4, v27
	v_rcp_f32_e32 v4, v22
	s_nop 0
	v_mul_f32_e32 v12, v4, v12
	v_mul_f32_e32 v11, v4, v60
	v_mul_f32_e32 v25, v4, v44
	v_mul_f32_e32 v22, v4, v28
	v_rcp_f32_e32 v4, v23
	s_nop 0
	v_mul_f32_e32 v28, v4, v45
	ds_read_b128 v[42:45], v0 offset:96
	v_mul_f32_e32 v19, v4, v13
	v_mul_f32_e32 v27, v4, v61
	v_mul_f32_e32 v23, v4, v29
	s_waitcnt lgkmcnt(0)
	v_rcp_f32_e32 v0, v42
	s_nop 0
	v_mul_f32_e32 v42, v0, v14
	v_mul_f32_e32 v13, v0, v62
	v_mul_f32_e32 v46, v0, v46
	v_mul_f32_e32 v14, v0, v30
	v_rcp_f32_e32 v0, v43
	s_nop 0
	v_mul_f32_e32 v30, v0, v15
	v_mul_f32_e32 v61, v0, v63
	v_mul_f32_e32 v78, v0, v47
	v_mul_f32_e32 v24, v0, v31
	v_rcp_f32_e32 v0, v44
	v_mov_b32_e32 v15, v188
	v_mul_f32_e32 v16, v0, v16
	v_mul_f32_e32 v43, v0, v64
	v_mul_f32_e32 v56, v0, v48
	v_mul_f32_e32 v31, v0, v32
	v_rcp_f32_e32 v0, v45
	s_nop 0
	v_mul_f32_e32 v45, v0, v17
	v_mul_f32_e32 v17, v0, v65
	v_mul_f32_e32 v79, v0, v49
	v_mul_f32_e32 v32, v0, v33
	v_and_b32_e32 v0, 31, v15
	v_lshl_add_u32 v15, v15, 4, 0
	v_add_u32_e32 v92, 0x11000, v15
	ds_read_b128 v[62:65], v92
	ds_read_b128 v[94:97], v92 offset:8192
	v_lshlrev_b32_e32 v6, 2, v0
	global_load_dword v0, v6, s[0:1]
	global_load_dword v4, v6, s[0:1] offset:128
	global_load_dword v5, v6, s[0:1] offset:256
	s_waitcnt lgkmcnt(1)
	v_lshlrev_b32_e32 v15, 16, v62
	v_fma_f32 v87, -v202, v2, v15
	v_and_b32_e32 v2, 0xffff0000, v62
	v_fma_f32 v33, -v202, v3, v2
	v_lshlrev_b32_e32 v2, 16, v63
	v_fma_f32 v39, -v202, v50, v2
	v_and_b32_e32 v2, 0xffff0000, v63
	v_fma_f32 v49, -v202, v82, v2
	v_lshlrev_b32_e32 v2, 16, v64
	v_fma_f32 v58, -v202, v37, v2
	v_and_b32_e32 v2, 0xffff0000, v64
	v_fma_f32 v67, -v202, v54, v2
	v_lshlrev_b32_e32 v2, 16, v65
	v_fma_f32 v64, -v202, v55, v2
	v_and_b32_e32 v2, 0xffff0000, v65
	v_fma_f32 v54, -v202, v86, v2
	s_waitcnt lgkmcnt(0)
	v_lshlrev_b32_e32 v2, 16, v94
	v_fma_f32 v47, -v202, v7, v2
	v_and_b32_e32 v2, 0xffff0000, v94
	v_fma_f32 v37, -v202, v9, v2
	v_lshlrev_b32_e32 v2, 16, v95
	v_fma_f32 v29, -v202, v12, v2
	v_and_b32_e32 v2, 0xffff0000, v95
	v_fma_f32 v19, -v202, v19, v2
	v_lshlrev_b32_e32 v2, 16, v96
	v_fma_f32 v15, -v202, v42, v2
	v_and_b32_e32 v2, 0xffff0000, v96
	v_fma_f32 v9, -v202, v30, v2
	v_lshlrev_b32_e32 v2, 16, v97
	v_fma_f32 v7, -v202, v16, v2
	v_and_b32_e32 v2, 0xffff0000, v97
	ds_read_b128 v[94:97], v92 offset:16384
	global_load_dword v6, v6, s[0:1] offset:384
	v_mul_f32_e32 v83, v33, v33
	v_mul_f32_e32 v50, v49, v49
	v_mul_f32_e32 v68, v67, v67
	s_waitcnt lgkmcnt(0)
	v_lshlrev_b32_e32 v16, 16, v94
	v_fma_f32 v89, -v202, v69, v16
	v_and_b32_e32 v16, 0xffff0000, v94
	v_fma_f32 v86, -v202, v51, v16
	v_lshlrev_b32_e32 v16, 16, v95
	v_fma_f32 v42, -v202, v72, v16
	v_and_b32_e32 v16, 0xffff0000, v95
	v_fma_f32 v51, -v202, v74, v16
	v_lshlrev_b32_e32 v16, 16, v96
	v_fma_f32 v59, -v202, v80, v16
	v_and_b32_e32 v16, 0xffff0000, v96
	v_fma_f32 v69, -v202, v38, v16
	v_lshlrev_b32_e32 v16, 16, v97
	v_fma_f32 v72, -v202, v88, v16
	v_and_b32_e32 v16, 0xffff0000, v97
	ds_read_b128 v[94:97], v92 offset:24576
	v_fma_f32 v63, -v202, v57, v16
	v_mul_f32_e32 v91, v89, v89
	v_fmac_f32_e32 v91, v87, v87
	v_fmac_f32_e32 v83, v86, v86
	s_waitcnt lgkmcnt(0)
	v_lshlrev_b32_e32 v16, 16, v94
	v_fma_f32 v57, -v202, v8, v16
	v_and_b32_e32 v8, 0xffff0000, v94
	v_fma_f32 v48, -v202, v21, v8
	v_lshlrev_b32_e32 v8, 16, v95
	v_fma_f32 v38, -v202, v11, v8
	v_and_b32_e32 v8, 0xffff0000, v95
	v_fma_f32 v30, -v202, v27, v8
	v_lshlrev_b32_e32 v8, 16, v96
	v_fma_f32 v21, -v202, v13, v8
	v_and_b32_e32 v8, 0xffff0000, v96
	v_fma_f32 v16, -v202, v61, v8
	v_lshlrev_b32_e32 v8, 16, v97
	v_fma_f32 v11, -v202, v43, v8
	v_and_b32_e32 v8, 0xffff0000, v97
	ds_read_b128 v[94:97], v92 offset:32768
	v_fma_f32 v8, -v202, v17, v8
	v_mul_f32_e32 v82, v42, v42
	v_fmac_f32_e32 v82, v39, v39
	v_fmac_f32_e32 v50, v51, v51
	s_waitcnt lgkmcnt(0)
; __global__ void __launch_bounds__(NTHR) mega_fwd(Params p) {
;     ...
;                       for (int k = 0; k < 8; ++k) { const int d = k >> 1, r0 = 8 * (k & 1); const v4u w = STv[k * 512];
; #pragma unroll
;                           for (int i = 0; i < 4; ++i) { const unsigned wi = i == 0 ? w.x : (i == 1 ? w.y : (i == 2 ? w.z : w.w));
;                               const float va = bf2f((unsigned short)(wi & 0xffffu)) - lam * o[d][r0 + 2 * i], vb = bf2f((unsigned short)(wi >> 16)) - lam * o[d][r0 + 2 * i + 1];
;                               o[d][r0 + 2 * i] = va; o[d][r0 + 2 * i + 1] = vb; ss[r0 + 2 * i] += va * va; ss[r0 + 2 * i + 1] += vb * vb; } }
; #pragma unroll
;                       for (int r = 0; r < 16; ++r) { float q = ss[r]; q += __shfl_xor(q, 1); q += __shfl_xor(q, 2); q += __shfl_xor(q, 4); q += __shfl_xor(q, 8); q += __shfl_xor(q, 16);
;                           const float rstd = 1.0f / sqrtf(q * (1.0f / 128.0f) + EPS);
; #pragma unroll
;                           for (int d = 0; d < 4; ++d) o[d][r] *= rstd * gsub[d]; } }
	v_lshlrev_b32_e32 v17, 16, v94
	v_fma_f32 v93, -v202, v70, v17
	v_and_b32_e32 v17, 0xffff0000, v94
	v_fma_f32 v90, -v202, v71, v17
	v_lshlrev_b32_e32 v17, 16, v95
	v_fma_f32 v88, -v202, v73, v17
	v_and_b32_e32 v17, 0xffff0000, v95
	v_fma_f32 v80, -v202, v53, v17
	v_lshlrev_b32_e32 v17, 16, v96
	v_fma_f32 v61, -v202, v76, v17
	v_and_b32_e32 v17, 0xffff0000, v96
	v_fma_f32 v70, -v202, v81, v17
	v_lshlrev_b32_e32 v17, 16, v97
	v_fma_f32 v76, -v202, v84, v17
	v_and_b32_e32 v17, 0xffff0000, v97
	ds_read_b128 v[94:97], v92 offset:40960
	v_fma_f32 v73, -v202, v85, v17
	v_fmac_f32_e32 v91, v93, v93
	v_fmac_f32_e32 v83, v90, v90
	s_waitcnt vmcnt(3)
	v_mul_f32_e32 v0, v201, v0
	s_waitcnt lgkmcnt(0)
	v_lshlrev_b32_e32 v17, 16, v94
	v_fma_f32 v71, -v202, v10, v17
	v_and_b32_e32 v10, 0xffff0000, v94
	v_fma_f32 v62, -v202, v35, v10
	v_lshlrev_b32_e32 v10, 16, v95
	v_fma_f32 v53, -v202, v25, v10
	v_and_b32_e32 v10, 0xffff0000, v95
	v_fma_f32 v43, -v202, v28, v10
	v_lshlrev_b32_e32 v10, 16, v96
	v_fma_f32 v35, -v202, v46, v10
	v_and_b32_e32 v10, 0xffff0000, v96
	v_fma_f32 v25, -v202, v78, v10
	v_lshlrev_b32_e32 v10, 16, v97
	v_fma_f32 v17, -v202, v56, v10
	v_and_b32_e32 v10, 0xffff0000, v97
	ds_read_b128 v[94:97], v92 offset:49152
	v_fma_f32 v10, -v202, v79, v10
	s_waitcnt vmcnt(2)
	v_mul_f32_e32 v4, v201, v4
	s_waitcnt vmcnt(1)
	v_mul_f32_e32 v5, v201, v5
	s_waitcnt vmcnt(0)
	v_mul_f32_e32 v6, v201, v6
	s_waitcnt lgkmcnt(0)
	v_lshlrev_b32_e32 v28, 16, v94
	v_fma_f32 v85, -v202, v34, v28
	v_and_b32_e32 v28, 0xffff0000, v94
	v_fma_f32 v34, -v202, v66, v28
	v_lshlrev_b32_e32 v28, 16, v95
	v_fma_f32 v84, -v202, v36, v28
	v_and_b32_e32 v28, 0xffff0000, v95
	v_fma_f32 v52, -v202, v52, v28
	v_lshlrev_b32_e32 v28, 16, v96
	v_fma_f32 v81, -v202, v75, v28
	v_and_b32_e32 v28, 0xffff0000, v96
	v_fma_f32 v79, -v202, v77, v28
	v_lshlrev_b32_e32 v28, 16, v97
	v_fma_f32 v78, -v202, v40, v28
	v_and_b32_e32 v28, 0xffff0000, v97
	ds_read_b128 v[94:97], v92 offset:57344
	v_fma_f32 v77, -v202, v41, v28
	v_fmac_f32_e32 v91, v85, v85
	v_fmac_f32_e32 v83, v34, v34
	v_fmac_f32_e32 v82, v88, v88
	s_waitcnt lgkmcnt(0)
	v_lshlrev_b32_e32 v28, 16, v94
	v_fma_f32 v75, -v202, v18, v28
	v_and_b32_e32 v18, 0xffff0000, v94
	v_fma_f32 v66, -v202, v20, v18
	ds_bpermute_b32 v20, v162, v91
	v_lshlrev_b32_e32 v18, 16, v95
	v_fma_f32 v56, -v202, v22, v18
	v_and_b32_e32 v18, 0xffff0000, v95
	v_fma_f32 v46, -v202, v23, v18
	s_waitcnt lgkmcnt(0)
	v_add_f32_e32 v20, v91, v20
	ds_bpermute_b32 v22, v178, v20
	v_lshlrev_b32_e32 v18, 16, v96
	v_fma_f32 v36, -v202, v14, v18
	v_and_b32_e32 v14, 0xffff0000, v96
	v_fma_f32 v28, -v202, v24, v14
	s_waitcnt lgkmcnt(0)
	v_add_f32_e32 v20, v20, v22
	ds_bpermute_b32 v22, v179, v20
	v_lshlrev_b32_e32 v14, 16, v97
	v_fma_f32 v18, -v202, v31, v14
	v_and_b32_e32 v14, 0xffff0000, v97
	v_fma_f32 v14, -v202, v32, v14
	s_waitcnt lgkmcnt(0)
	v_add_f32_e32 v20, v20, v22
	ds_bpermute_b32 v22, v180, v20
	v_fmac_f32_e32 v82, v84, v84
	v_fmac_f32_e32 v50, v80, v80
	v_fmac_f32_e32 v50, v52, v52
	v_mul_f32_e32 v60, v59, v59
	s_waitcnt lgkmcnt(0)
	v_add_f32_e32 v20, v20, v22
	ds_bpermute_b32 v22, v187, v20
	v_fmac_f32_e32 v60, v58, v58
	v_fmac_f32_e32 v60, v61, v61
	v_fmac_f32_e32 v60, v81, v81
	v_fmac_f32_e32 v68, v69, v69
	s_waitcnt lgkmcnt(0)
	v_add_f32_e32 v20, v20, v22
	v_fmamk_f32 v20, v20, 0x3c000000, v189
	v_cmp_gt_f32_e32 vcc, s2, v20
	v_mul_f32_e32 v22, 0x4f800000, v20
	v_fmac_f32_e32 v68, v70, v70
	v_cndmask_b32_e32 v20, v20, v22, vcc
	v_sqrt_f32_e32 v22, v20
	v_fmac_f32_e32 v68, v79, v79
	v_mul_f32_e32 v74, v72, v72
	v_fmac_f32_e32 v74, v64, v64
	v_add_u32_e32 v23, -1, v22
	v_fma_f32 v24, -v23, v22, v20
	v_cmp_ge_f32_e64 s[0:1], 0, v24
	v_add_u32_e32 v24, 1, v22
	v_fmac_f32_e32 v74, v76, v76
	v_cndmask_b32_e64 v23, v22, v23, s[0:1]
	v_fma_f32 v22, -v24, v22, v20
	v_cmp_lt_f32_e64 s[0:1], 0, v22
	v_fmac_f32_e32 v74, v78, v78
	v_mul_f32_e32 v55, v54, v54
	v_cndmask_b32_e64 v22, v23, v24, s[0:1]
	v_mul_f32_e32 v23, 0x37800000, v22
	v_cndmask_b32_e32 v22, v22, v23, vcc
	v_cmp_class_f32_e32 vcc, v20, v190
	v_fmac_f32_e32 v55, v63, v63
	v_fmac_f32_e32 v55, v73, v73
	v_cndmask_b32_e32 v20, v22, v20, vcc
	v_div_scale_f32 v22, s[0:1], v20, v20, 1.0
	v_rcp_f32_e32 v23, v22
	v_fmac_f32_e32 v55, v77, v77
	v_mul_f32_e32 v65, v57, v57
	v_fmac_f32_e32 v65, v47, v47
	v_fma_f32 v24, -v22, v23, 1.0
	v_fmac_f32_e32 v23, v24, v23
	v_div_scale_f32 v24, vcc, 1.0, v20, 1.0
	v_mul_f32_e32 v31, v24, v23
	v_fma_f32 v32, -v22, v31, v24
	v_fmac_f32_e32 v31, v32, v23
	v_fma_f32 v22, -v22, v31, v24
	v_div_fmas_f32 v22, v22, v23, v31
	ds_bpermute_b32 v31, v162, v83
	v_div_fixup_f32 v24, v22, v20, 1.0
	v_mul_f32_e32 v20, v24, v0
	v_mul_f32_e32 v22, v24, v4
	v_mul_f32_e32 v23, v24, v5
	s_waitcnt lgkmcnt(0)
	v_add_f32_e32 v31, v83, v31
	ds_bpermute_b32 v32, v178, v31
	v_mul_f32_e32 v24, v24, v6
	v_mul_f32_e32 v24, v24, v85
	v_fmac_f32_e32 v65, v71, v71
	v_fmac_f32_e32 v65, v75, v75
	s_waitcnt lgkmcnt(0)
	v_add_f32_e32 v31, v31, v32
	ds_bpermute_b32 v32, v179, v31
	v_mul_f32_e32 v44, v37, v37
	v_fmac_f32_e32 v44, v48, v48
	v_fmac_f32_e32 v44, v62, v62
	v_fmac_f32_e32 v44, v66, v66
	s_waitcnt lgkmcnt(0)
	v_add_f32_e32 v31, v31, v32
	ds_bpermute_b32 v32, v180, v31
	v_fma_f32 v2, -v202, v45, v2
	v_mul_f32_e32 v45, v38, v38
	v_fmac_f32_e32 v45, v29, v29
	v_fmac_f32_e32 v45, v53, v53
	s_waitcnt lgkmcnt(0)
	v_add_f32_e32 v31, v31, v32
	ds_bpermute_b32 v32, v187, v31
	v_fmac_f32_e32 v45, v56, v56
	v_mul_f32_e32 v26, v19, v19
	v_fmac_f32_e32 v26, v30, v30
	v_fmac_f32_e32 v26, v43, v43
	s_waitcnt lgkmcnt(0)
; __global__ void __launch_bounds__(NTHR) mega_fwd(Params p) {
;     ...
; #pragma unroll
;                       for (int r = 0; r < 16; ++r) { float q = ss[r]; q += __shfl_xor(q, 1); q += __shfl_xor(q, 2); q += __shfl_xor(q, 4); q += __shfl_xor(q, 8); q += __shfl_xor(q, 16);
;                           const float rstd = 1.0f / sqrtf(q * (1.0f / 128.0f) + EPS);
; #pragma unroll
;                           for (int d = 0; d < 4; ++d) o[d][r] *= rstd * gsub[d]; } }
	v_add_f32_e32 v31, v31, v32
	v_fmamk_f32 v31, v31, 0x3c000000, v189
	v_cmp_gt_f32_e32 vcc, s2, v31
	v_mul_f32_e32 v32, 0x4f800000, v31
	v_fmac_f32_e32 v26, v46, v46
	v_cndmask_b32_e32 v31, v31, v32, vcc
	v_sqrt_f32_e32 v32, v31
	v_mul_f32_e32 v27, v21, v21
	v_fmac_f32_e32 v27, v15, v15
	v_fmac_f32_e32 v27, v35, v35
	v_add_u32_e32 v40, -1, v32
	v_fma_f32 v41, -v40, v32, v31
	v_cmp_ge_f32_e64 s[0:1], 0, v41
	v_add_u32_e32 v41, 1, v32
	v_fmac_f32_e32 v27, v36, v36
	v_cndmask_b32_e64 v40, v32, v40, s[0:1]
	v_fma_f32 v32, -v41, v32, v31
	v_cmp_lt_f32_e64 s[0:1], 0, v32
	v_mul_f32_e32 v12, v9, v9
	v_fmac_f32_e32 v12, v16, v16
	v_cndmask_b32_e64 v32, v40, v41, s[0:1]
	v_mul_f32_e32 v40, 0x37800000, v32
	v_cndmask_b32_e32 v32, v32, v40, vcc
	v_cmp_class_f32_e32 vcc, v31, v190
	v_fmac_f32_e32 v12, v25, v25
	v_fmac_f32_e32 v12, v28, v28
	v_cndmask_b32_e32 v31, v32, v31, vcc
	v_div_scale_f32 v32, s[0:1], v31, v31, 1.0
	v_rcp_f32_e32 v40, v32
	v_mul_f32_e32 v13, v11, v11
	v_fmac_f32_e32 v13, v7, v7
	v_fmac_f32_e32 v13, v17, v17
	v_fma_f32 v41, -v32, v40, 1.0
	v_fmac_f32_e32 v40, v41, v40
	v_div_scale_f32 v41, vcc, 1.0, v31, 1.0
	v_mul_f32_e32 v83, v41, v40
	v_fma_f32 v85, -v32, v83, v41
	v_fmac_f32_e32 v83, v85, v40
	v_fma_f32 v32, -v32, v83, v41
	v_div_fmas_f32 v32, v32, v40, v83
	v_div_fixup_f32 v40, v32, v31, 1.0
	v_mul_f32_e32 v31, v40, v0
	v_mul_f32_e32 v31, v31, v33
	v_mul_f32_e32 v32, v40, v4
	v_mul_f32_e32 v33, v40, v5
	v_mul_f32_e32 v40, v40, v6
	v_mul_f32_e32 v34, v40, v34
	ds_bpermute_b32 v40, v162, v82
	v_mul_f32_e32 v32, v32, v86
	v_fmac_f32_e32 v13, v18, v18
	v_mul_f32_e32 v3, v2, v2
	v_fmac_f32_e32 v3, v8, v8
	s_waitcnt lgkmcnt(0)
	v_add_f32_e32 v40, v82, v40
	ds_bpermute_b32 v41, v178, v40
	v_fmac_f32_e32 v3, v10, v10
	v_fmac_f32_e32 v3, v14, v14
	v_mul_f32_e32 v20, v20, v87
	v_mul_f32_e32 v22, v22, v89
	s_waitcnt lgkmcnt(0)
	v_add_f32_e32 v40, v40, v41
	ds_bpermute_b32 v41, v179, v40
	v_mul_f32_e32 v23, v23, v93
	v_mul_f32_e32 v33, v33, v90
	s_waitcnt lgkmcnt(0)
	v_add_f32_e32 v40, v40, v41
	ds_bpermute_b32 v41, v180, v40
	s_waitcnt lgkmcnt(0)
	v_add_f32_e32 v40, v40, v41
	ds_bpermute_b32 v41, v187, v40
	s_waitcnt lgkmcnt(0)
	v_add_f32_e32 v40, v40, v41
	v_fmamk_f32 v40, v40, 0x3c000000, v189
	v_cmp_gt_f32_e32 vcc, s2, v40
	v_mul_f32_e32 v41, 0x4f800000, v40
	s_nop 0
	v_cndmask_b32_e32 v40, v40, v41, vcc
	v_sqrt_f32_e32 v41, v40
	s_nop 0
	v_add_u32_e32 v82, -1, v41
	v_fma_f32 v83, -v82, v41, v40
	v_cmp_ge_f32_e64 s[0:1], 0, v83
	v_add_u32_e32 v83, 1, v41
	s_nop 0
	v_cndmask_b32_e64 v82, v41, v82, s[0:1]
	v_fma_f32 v41, -v83, v41, v40
	v_cmp_lt_f32_e64 s[0:1], 0, v41
	s_nop 1
	v_cndmask_b32_e64 v41, v82, v83, s[0:1]
	v_mul_f32_e32 v82, 0x37800000, v41
	v_cndmask_b32_e32 v41, v41, v82, vcc
	v_cmp_class_f32_e32 vcc, v40, v190
	s_nop 1
	v_cndmask_b32_e32 v40, v41, v40, vcc
	v_div_scale_f32 v41, s[0:1], v40, v40, 1.0
	v_rcp_f32_e32 v82, v41
	s_nop 0
	v_fma_f32 v83, -v41, v82, 1.0
	v_fmac_f32_e32 v82, v83, v82
	v_div_scale_f32 v83, vcc, 1.0, v40, 1.0
	v_mul_f32_e32 v85, v83, v82
	v_fma_f32 v86, -v41, v85, v83
	v_fmac_f32_e32 v85, v86, v82
	v_fma_f32 v41, -v41, v85, v83
	v_div_fmas_f32 v41, v41, v82, v85
	v_div_fixup_f32 v82, v41, v40, 1.0
	v_mul_f32_e32 v40, v82, v0
	v_mul_f32_e32 v39, v40, v39
	v_mul_f32_e32 v40, v82, v4
	v_mul_f32_e32 v40, v40, v42
	v_mul_f32_e32 v41, v82, v5
	v_mul_f32_e32 v42, v82, v6
	ds_bpermute_b32 v82, v162, v50
	v_mul_f32_e32 v42, v42, v84
	v_mul_f32_e32 v41, v41, v88
	s_waitcnt lgkmcnt(0)
	v_add_f32_e32 v50, v50, v82
	ds_bpermute_b32 v82, v178, v50
	s_waitcnt lgkmcnt(0)
	v_add_f32_e32 v50, v50, v82
	ds_bpermute_b32 v82, v179, v50
	s_waitcnt lgkmcnt(0)
	v_add_f32_e32 v50, v50, v82
	ds_bpermute_b32 v82, v180, v50
	s_waitcnt lgkmcnt(0)
	v_add_f32_e32 v50, v50, v82
	ds_bpermute_b32 v82, v187, v50
	s_waitcnt lgkmcnt(0)
	v_add_f32_e32 v50, v50, v82
	v_fmamk_f32 v50, v50, 0x3c000000, v189
	v_cmp_gt_f32_e32 vcc, s2, v50
	v_mul_f32_e32 v82, 0x4f800000, v50
	s_nop 0
	v_cndmask_b32_e32 v50, v50, v82, vcc
	v_sqrt_f32_e32 v82, v50
	s_nop 0
	v_add_u32_e32 v83, -1, v82
	v_fma_f32 v84, -v83, v82, v50
	v_cmp_ge_f32_e64 s[0:1], 0, v84
	v_add_u32_e32 v84, 1, v82
	s_nop 0
	v_cndmask_b32_e64 v83, v82, v83, s[0:1]
	v_fma_f32 v82, -v84, v82, v50
	v_cmp_lt_f32_e64 s[0:1], 0, v82
	s_nop 1
	v_cndmask_b32_e64 v82, v83, v84, s[0:1]
	v_mul_f32_e32 v83, 0x37800000, v82
	v_cndmask_b32_e32 v82, v82, v83, vcc
	v_cmp_class_f32_e32 vcc, v50, v190
	s_nop 1
	v_cndmask_b32_e32 v50, v82, v50, vcc
	v_div_scale_f32 v82, s[0:1], v50, v50, 1.0
	v_rcp_f32_e32 v83, v82
	s_nop 0
	v_fma_f32 v84, -v82, v83, 1.0
	v_fmac_f32_e32 v83, v84, v83
	v_div_scale_f32 v84, vcc, 1.0, v50, 1.0
	v_mul_f32_e32 v85, v84, v83
	v_fma_f32 v86, -v82, v85, v84
	v_fmac_f32_e32 v85, v86, v83
	v_fma_f32 v82, -v82, v85, v84
	v_div_fmas_f32 v82, v82, v83, v85
	v_div_fixup_f32 v82, v82, v50, 1.0
	v_mul_f32_e32 v50, v82, v0
	v_mul_f32_e32 v49, v50, v49
	v_mul_f32_e32 v50, v82, v4
	v_mul_f32_e32 v50, v50, v51
	v_mul_f32_e32 v51, v82, v5
	v_mul_f32_e32 v51, v51, v80
	v_mul_f32_e32 v80, v82, v6
	v_mul_f32_e32 v52, v80, v52
	ds_bpermute_b32 v80, v162, v60
	s_waitcnt lgkmcnt(0)
	v_add_f32_e32 v60, v60, v80
	ds_bpermute_b32 v80, v178, v60
	s_waitcnt lgkmcnt(0)
	v_add_f32_e32 v60, v60, v80
	ds_bpermute_b32 v80, v179, v60
	s_waitcnt lgkmcnt(0)
	v_add_f32_e32 v60, v60, v80
	ds_bpermute_b32 v80, v180, v60
	s_waitcnt lgkmcnt(0)
	v_add_f32_e32 v60, v60, v80
	ds_bpermute_b32 v80, v187, v60
	s_waitcnt lgkmcnt(0)
; __global__ void __launch_bounds__(NTHR) mega_fwd(Params p) {
;     ...
; #pragma unroll
;                       for (int r = 0; r < 16; ++r) { float q = ss[r]; q += __shfl_xor(q, 1); q += __shfl_xor(q, 2); q += __shfl_xor(q, 4); q += __shfl_xor(q, 8); q += __shfl_xor(q, 16);
;                           const float rstd = 1.0f / sqrtf(q * (1.0f / 128.0f) + EPS);
; #pragma unroll
;                           for (int d = 0; d < 4; ++d) o[d][r] *= rstd * gsub[d]; } }
	v_add_f32_e32 v60, v60, v80
	v_fmamk_f32 v60, v60, 0x3c000000, v189
	v_cmp_gt_f32_e32 vcc, s2, v60
	v_mul_f32_e32 v80, 0x4f800000, v60
	s_nop 0
	v_cndmask_b32_e32 v60, v60, v80, vcc
	v_sqrt_f32_e32 v80, v60
	s_nop 0
	v_add_u32_e32 v82, -1, v80
	v_fma_f32 v83, -v82, v80, v60
	v_cmp_ge_f32_e64 s[0:1], 0, v83
	v_add_u32_e32 v83, 1, v80
	s_nop 0
	v_cndmask_b32_e64 v82, v80, v82, s[0:1]
	v_fma_f32 v80, -v83, v80, v60
	v_cmp_lt_f32_e64 s[0:1], 0, v80
	s_nop 1
	v_cndmask_b32_e64 v80, v82, v83, s[0:1]
	v_mul_f32_e32 v82, 0x37800000, v80
	v_cndmask_b32_e32 v80, v80, v82, vcc
	v_cmp_class_f32_e32 vcc, v60, v190
	s_nop 1
	v_cndmask_b32_e32 v60, v80, v60, vcc
	v_div_scale_f32 v80, s[0:1], v60, v60, 1.0
	v_rcp_f32_e32 v82, v80
	s_nop 0
	v_fma_f32 v83, -v80, v82, 1.0
	v_fmac_f32_e32 v82, v83, v82
	v_div_scale_f32 v83, vcc, 1.0, v60, 1.0
	v_mul_f32_e32 v84, v83, v82
	v_fma_f32 v85, -v80, v84, v83
	v_fmac_f32_e32 v84, v85, v82
	v_fma_f32 v80, -v80, v84, v83
	v_div_fmas_f32 v80, v80, v82, v84
	v_div_fixup_f32 v80, v80, v60, 1.0
	v_mul_f32_e32 v60, v80, v0
	v_mul_f32_e32 v58, v60, v58
	v_mul_f32_e32 v60, v80, v4
	v_mul_f32_e32 v59, v60, v59
	v_mul_f32_e32 v60, v80, v5
	v_mul_f32_e32 v60, v60, v61
	v_mul_f32_e32 v61, v80, v6
	ds_bpermute_b32 v80, v162, v68
	v_mul_f32_e32 v61, v61, v81
	s_waitcnt lgkmcnt(0)
	v_add_f32_e32 v68, v68, v80
	ds_bpermute_b32 v80, v178, v68
	s_waitcnt lgkmcnt(0)
	v_add_f32_e32 v68, v68, v80
	ds_bpermute_b32 v80, v179, v68
	s_waitcnt lgkmcnt(0)
	v_add_f32_e32 v68, v68, v80
	ds_bpermute_b32 v80, v180, v68
	s_waitcnt lgkmcnt(0)
	v_add_f32_e32 v68, v68, v80
	ds_bpermute_b32 v80, v187, v68
	s_waitcnt lgkmcnt(0)
	v_add_f32_e32 v68, v68, v80
	v_fmamk_f32 v68, v68, 0x3c000000, v189
	v_cmp_gt_f32_e32 vcc, s2, v68
	v_mul_f32_e32 v80, 0x4f800000, v68
	s_nop 0
	v_cndmask_b32_e32 v68, v68, v80, vcc
	v_sqrt_f32_e32 v80, v68
	s_nop 0
	v_add_u32_e32 v81, -1, v80
	v_fma_f32 v82, -v81, v80, v68
	v_cmp_ge_f32_e64 s[0:1], 0, v82
	v_add_u32_e32 v82, 1, v80
	s_nop 0
	v_cndmask_b32_e64 v81, v80, v81, s[0:1]
	v_fma_f32 v80, -v82, v80, v68
	v_cmp_lt_f32_e64 s[0:1], 0, v80
	s_nop 1
	v_cndmask_b32_e64 v80, v81, v82, s[0:1]
	v_mul_f32_e32 v81, 0x37800000, v80
	v_cndmask_b32_e32 v80, v80, v81, vcc
	v_cmp_class_f32_e32 vcc, v68, v190
	s_nop 1
	v_cndmask_b32_e32 v68, v80, v68, vcc
	v_div_scale_f32 v80, s[0:1], v68, v68, 1.0
	v_rcp_f32_e32 v81, v80
	s_nop 0
	v_fma_f32 v82, -v80, v81, 1.0
	v_fmac_f32_e32 v81, v82, v81
	v_div_scale_f32 v82, vcc, 1.0, v68, 1.0
	v_mul_f32_e32 v83, v82, v81
	v_fma_f32 v84, -v80, v83, v82
	v_fmac_f32_e32 v83, v84, v81
	v_fma_f32 v80, -v80, v83, v82
	v_div_fmas_f32 v80, v80, v81, v83
	v_div_fixup_f32 v80, v80, v68, 1.0
	v_mul_f32_e32 v68, v80, v0
	v_mul_f32_e32 v67, v68, v67
	v_mul_f32_e32 v68, v80, v4
	v_mul_f32_e32 v68, v68, v69
	v_mul_f32_e32 v69, v80, v5
	v_mul_f32_e32 v69, v69, v70
	v_mul_f32_e32 v70, v80, v6
	v_mul_f32_e32 v70, v70, v79
	ds_bpermute_b32 v79, v162, v74
	s_waitcnt lgkmcnt(0)
	v_add_f32_e32 v74, v74, v79
	ds_bpermute_b32 v79, v178, v74
	s_waitcnt lgkmcnt(0)
	v_add_f32_e32 v74, v74, v79
	ds_bpermute_b32 v79, v179, v74
	s_waitcnt lgkmcnt(0)
	v_add_f32_e32 v74, v74, v79
	ds_bpermute_b32 v79, v180, v74
	s_waitcnt lgkmcnt(0)
	v_add_f32_e32 v74, v74, v79
	ds_bpermute_b32 v79, v187, v74
	s_waitcnt lgkmcnt(0)
	v_add_f32_e32 v74, v74, v79
	v_fmamk_f32 v74, v74, 0x3c000000, v189
	v_cmp_gt_f32_e32 vcc, s2, v74
	v_mul_f32_e32 v79, 0x4f800000, v74
	s_nop 0
	v_cndmask_b32_e32 v74, v74, v79, vcc
	v_sqrt_f32_e32 v79, v74
	s_nop 0
	v_add_u32_e32 v80, -1, v79
	v_fma_f32 v81, -v80, v79, v74
	v_cmp_ge_f32_e64 s[0:1], 0, v81
	v_add_u32_e32 v81, 1, v79
	s_nop 0
	v_cndmask_b32_e64 v80, v79, v80, s[0:1]
	v_fma_f32 v79, -v81, v79, v74
	v_cmp_lt_f32_e64 s[0:1], 0, v79
	s_nop 1
	v_cndmask_b32_e64 v79, v80, v81, s[0:1]
	v_mul_f32_e32 v80, 0x37800000, v79
	v_cndmask_b32_e32 v79, v79, v80, vcc
	v_cmp_class_f32_e32 vcc, v74, v190
	s_nop 1
	v_cndmask_b32_e32 v74, v79, v74, vcc
	v_div_scale_f32 v79, s[0:1], v74, v74, 1.0
	v_rcp_f32_e32 v80, v79
	s_nop 0
	v_fma_f32 v81, -v79, v80, 1.0
	v_fmac_f32_e32 v80, v81, v80
	v_div_scale_f32 v81, vcc, 1.0, v74, 1.0
	v_mul_f32_e32 v82, v81, v80
	v_fma_f32 v83, -v79, v82, v81
	v_fmac_f32_e32 v82, v83, v80
	v_fma_f32 v79, -v79, v82, v81
	v_div_fmas_f32 v79, v79, v80, v82
	v_div_fixup_f32 v79, v79, v74, 1.0
	v_mul_f32_e32 v74, v79, v0
	v_mul_f32_e32 v64, v74, v64
	v_mul_f32_e32 v74, v79, v4
	v_mul_f32_e32 v72, v74, v72
	v_mul_f32_e32 v74, v79, v5
	v_mul_f32_e32 v74, v74, v76
	v_mul_f32_e32 v76, v79, v6
	v_mul_f32_e32 v76, v76, v78
	ds_bpermute_b32 v78, v162, v55
	s_waitcnt lgkmcnt(0)
	v_add_f32_e32 v55, v55, v78
	ds_bpermute_b32 v78, v178, v55
	s_waitcnt lgkmcnt(0)
	v_add_f32_e32 v55, v55, v78
	ds_bpermute_b32 v78, v179, v55
	s_waitcnt lgkmcnt(0)
	v_add_f32_e32 v55, v55, v78
	ds_bpermute_b32 v78, v180, v55
	s_waitcnt lgkmcnt(0)
	v_add_f32_e32 v55, v55, v78
	ds_bpermute_b32 v78, v187, v55
	s_waitcnt lgkmcnt(0)
	v_add_f32_e32 v55, v55, v78
	v_fmamk_f32 v55, v55, 0x3c000000, v189
	v_cmp_gt_f32_e32 vcc, s2, v55
	v_mul_f32_e32 v78, 0x4f800000, v55
	s_nop 0
	v_cndmask_b32_e32 v55, v55, v78, vcc
	v_sqrt_f32_e32 v78, v55
	s_nop 0
	v_add_u32_e32 v79, -1, v78
	v_fma_f32 v80, -v79, v78, v55
	v_cmp_ge_f32_e64 s[0:1], 0, v80
	v_add_u32_e32 v80, 1, v78
	s_nop 0
	v_cndmask_b32_e64 v79, v78, v79, s[0:1]
	v_fma_f32 v78, -v80, v78, v55
	v_cmp_lt_f32_e64 s[0:1], 0, v78
	s_nop 1
	v_cndmask_b32_e64 v78, v79, v80, s[0:1]
	v_mul_f32_e32 v79, 0x37800000, v78
	v_cndmask_b32_e32 v78, v78, v79, vcc
	v_cmp_class_f32_e32 vcc, v55, v190
	s_nop 1
	v_cndmask_b32_e32 v55, v78, v55, vcc
	v_div_scale_f32 v78, s[0:1], v55, v55, 1.0
	v_rcp_f32_e32 v79, v78
	s_nop 0
	v_fma_f32 v80, -v78, v79, 1.0
	v_fmac_f32_e32 v79, v80, v79
	v_div_scale_f32 v80, vcc, 1.0, v55, 1.0
	v_mul_f32_e32 v81, v80, v79
	v_fma_f32 v82, -v78, v81, v80
	v_fmac_f32_e32 v81, v82, v79
	v_fma_f32 v78, -v78, v81, v80
	v_div_fmas_f32 v78, v78, v79, v81
	v_div_fixup_f32 v78, v78, v55, 1.0
	v_mul_f32_e32 v55, v78, v0
	v_mul_f32_e32 v54, v55, v54
	v_mul_f32_e32 v55, v78, v4
	v_mul_f32_e32 v55, v55, v63
	v_mul_f32_e32 v63, v78, v5
	v_mul_f32_e32 v63, v63, v73
	v_mul_f32_e32 v73, v78, v6
	v_mul_f32_e32 v73, v73, v77
	ds_bpermute_b32 v77, v162, v65
	s_waitcnt lgkmcnt(0)
; __global__ void __launch_bounds__(NTHR) mega_fwd(Params p) {
;     ...
; #pragma unroll
;                       for (int r = 0; r < 16; ++r) { float q = ss[r]; q += __shfl_xor(q, 1); q += __shfl_xor(q, 2); q += __shfl_xor(q, 4); q += __shfl_xor(q, 8); q += __shfl_xor(q, 16);
;                           const float rstd = 1.0f / sqrtf(q * (1.0f / 128.0f) + EPS);
; #pragma unroll
;                           for (int d = 0; d < 4; ++d) o[d][r] *= rstd * gsub[d]; } }
	v_add_f32_e32 v65, v65, v77
	ds_bpermute_b32 v77, v178, v65
	s_waitcnt lgkmcnt(0)
	v_add_f32_e32 v65, v65, v77
	ds_bpermute_b32 v77, v179, v65
	s_waitcnt lgkmcnt(0)
	v_add_f32_e32 v65, v65, v77
	ds_bpermute_b32 v77, v180, v65
	s_waitcnt lgkmcnt(0)
	v_add_f32_e32 v65, v65, v77
	ds_bpermute_b32 v77, v187, v65
	s_waitcnt lgkmcnt(0)
	v_add_f32_e32 v65, v65, v77
	v_fmamk_f32 v65, v65, 0x3c000000, v189
	v_cmp_gt_f32_e32 vcc, s2, v65
	v_mul_f32_e32 v77, 0x4f800000, v65
	s_nop 0
	v_cndmask_b32_e32 v65, v65, v77, vcc
	v_sqrt_f32_e32 v77, v65
	s_nop 0
	v_add_u32_e32 v78, -1, v77
	v_fma_f32 v79, -v78, v77, v65
	v_cmp_ge_f32_e64 s[0:1], 0, v79
	v_add_u32_e32 v79, 1, v77
	s_nop 0
	v_cndmask_b32_e64 v78, v77, v78, s[0:1]
	v_fma_f32 v77, -v79, v77, v65
	v_cmp_lt_f32_e64 s[0:1], 0, v77
	s_nop 1
	v_cndmask_b32_e64 v77, v78, v79, s[0:1]
	v_mul_f32_e32 v78, 0x37800000, v77
	v_cndmask_b32_e32 v77, v77, v78, vcc
	v_cmp_class_f32_e32 vcc, v65, v190
	s_nop 1
	v_cndmask_b32_e32 v65, v77, v65, vcc
	v_div_scale_f32 v77, s[0:1], v65, v65, 1.0
	v_rcp_f32_e32 v78, v77
	s_nop 0
	v_fma_f32 v79, -v77, v78, 1.0
	v_fmac_f32_e32 v78, v79, v78
	v_div_scale_f32 v79, vcc, 1.0, v65, 1.0
	v_mul_f32_e32 v80, v79, v78
	v_fma_f32 v81, -v77, v80, v79
	v_fmac_f32_e32 v80, v81, v78
	v_fma_f32 v77, -v77, v80, v79
	v_div_fmas_f32 v77, v77, v78, v80
	v_div_fixup_f32 v77, v77, v65, 1.0
	v_mul_f32_e32 v65, v77, v0
	v_mul_f32_e32 v47, v65, v47
	v_mul_f32_e32 v65, v77, v4
	v_mul_f32_e32 v57, v65, v57
	v_mul_f32_e32 v65, v77, v5
	v_mul_f32_e32 v65, v65, v71
	v_mul_f32_e32 v71, v77, v6
	v_mul_f32_e32 v71, v71, v75
	ds_bpermute_b32 v75, v162, v44
	s_waitcnt lgkmcnt(0)
	v_add_f32_e32 v44, v44, v75
	ds_bpermute_b32 v75, v178, v44
	s_waitcnt lgkmcnt(0)
	v_add_f32_e32 v44, v44, v75
	ds_bpermute_b32 v75, v179, v44
	s_waitcnt lgkmcnt(0)
	v_add_f32_e32 v44, v44, v75
	ds_bpermute_b32 v75, v180, v44
	s_waitcnt lgkmcnt(0)
	v_add_f32_e32 v44, v44, v75
	ds_bpermute_b32 v75, v187, v44
	s_waitcnt lgkmcnt(0)
	v_add_f32_e32 v44, v44, v75
	v_fmamk_f32 v44, v44, 0x3c000000, v189
	v_cmp_gt_f32_e32 vcc, s2, v44
	v_mul_f32_e32 v75, 0x4f800000, v44
	s_nop 0
	v_cndmask_b32_e32 v44, v44, v75, vcc
	v_sqrt_f32_e32 v75, v44
	s_nop 0
	v_add_u32_e32 v77, -1, v75
	v_fma_f32 v78, -v77, v75, v44
	v_cmp_ge_f32_e64 s[0:1], 0, v78
	v_add_u32_e32 v78, 1, v75
	s_nop 0
	v_cndmask_b32_e64 v77, v75, v77, s[0:1]
	v_fma_f32 v75, -v78, v75, v44
	v_cmp_lt_f32_e64 s[0:1], 0, v75
	s_nop 1
	v_cndmask_b32_e64 v75, v77, v78, s[0:1]
	v_mul_f32_e32 v77, 0x37800000, v75
	v_cndmask_b32_e32 v75, v75, v77, vcc
	v_cmp_class_f32_e32 vcc, v44, v190
	s_nop 1
	v_cndmask_b32_e32 v44, v75, v44, vcc
	v_div_scale_f32 v75, s[0:1], v44, v44, 1.0
	v_rcp_f32_e32 v77, v75
	s_nop 0
	v_fma_f32 v78, -v75, v77, 1.0
	v_fmac_f32_e32 v77, v78, v77
	v_div_scale_f32 v78, vcc, 1.0, v44, 1.0
	v_mul_f32_e32 v79, v78, v77
	v_fma_f32 v80, -v75, v79, v78
	v_fmac_f32_e32 v79, v80, v77
	v_fma_f32 v75, -v75, v79, v78
	v_div_fmas_f32 v75, v75, v77, v79
	v_div_fixup_f32 v75, v75, v44, 1.0
	v_mul_f32_e32 v44, v75, v0
	v_mul_f32_e32 v37, v44, v37
	v_mul_f32_e32 v44, v75, v4
	v_mul_f32_e32 v44, v44, v48
	v_mul_f32_e32 v48, v75, v5
	v_mul_f32_e32 v48, v48, v62
	v_mul_f32_e32 v62, v75, v6
	v_mul_f32_e32 v62, v62, v66
	ds_bpermute_b32 v66, v162, v45
	s_waitcnt lgkmcnt(0)
	v_add_f32_e32 v45, v45, v66
	ds_bpermute_b32 v66, v178, v45
	s_waitcnt lgkmcnt(0)
	v_add_f32_e32 v45, v45, v66
	ds_bpermute_b32 v66, v179, v45
	s_waitcnt lgkmcnt(0)
	v_add_f32_e32 v45, v45, v66
	ds_bpermute_b32 v66, v180, v45
	s_waitcnt lgkmcnt(0)
	v_add_f32_e32 v45, v45, v66
	ds_bpermute_b32 v66, v187, v45
	s_waitcnt lgkmcnt(0)
	v_add_f32_e32 v45, v45, v66
	v_fmamk_f32 v45, v45, 0x3c000000, v189
	v_cmp_gt_f32_e32 vcc, s2, v45
	v_mul_f32_e32 v66, 0x4f800000, v45
	s_nop 0
	v_cndmask_b32_e32 v45, v45, v66, vcc
	v_sqrt_f32_e32 v66, v45
	s_nop 0
	v_add_u32_e32 v75, -1, v66
	v_fma_f32 v77, -v75, v66, v45
	v_cmp_ge_f32_e64 s[0:1], 0, v77
	v_add_u32_e32 v77, 1, v66
	s_nop 0
	v_cndmask_b32_e64 v75, v66, v75, s[0:1]
	v_fma_f32 v66, -v77, v66, v45
	v_cmp_lt_f32_e64 s[0:1], 0, v66
	s_nop 1
	v_cndmask_b32_e64 v66, v75, v77, s[0:1]
	v_mul_f32_e32 v75, 0x37800000, v66
	v_cndmask_b32_e32 v66, v66, v75, vcc
	v_cmp_class_f32_e32 vcc, v45, v190
	s_nop 1
	v_cndmask_b32_e32 v45, v66, v45, vcc
	v_div_scale_f32 v66, s[0:1], v45, v45, 1.0
	v_rcp_f32_e32 v75, v66
	s_nop 0
	v_fma_f32 v77, -v66, v75, 1.0
	v_fmac_f32_e32 v75, v77, v75
	v_div_scale_f32 v77, vcc, 1.0, v45, 1.0
	v_mul_f32_e32 v78, v77, v75
	v_fma_f32 v79, -v66, v78, v77
	v_fmac_f32_e32 v78, v79, v75
	v_fma_f32 v66, -v66, v78, v77
	v_div_fmas_f32 v66, v66, v75, v78
	v_div_fixup_f32 v66, v66, v45, 1.0
	v_mul_f32_e32 v45, v66, v0
	v_mul_f32_e32 v29, v45, v29
	v_mul_f32_e32 v45, v66, v4
	v_mul_f32_e32 v38, v45, v38
	v_mul_f32_e32 v45, v66, v5
	v_mul_f32_e32 v45, v45, v53
	v_mul_f32_e32 v53, v66, v6
	v_mul_f32_e32 v53, v53, v56
	ds_bpermute_b32 v56, v162, v26
	s_waitcnt lgkmcnt(0)
	v_add_f32_e32 v26, v26, v56
	ds_bpermute_b32 v56, v178, v26
	s_waitcnt lgkmcnt(0)
	v_add_f32_e32 v26, v26, v56
	ds_bpermute_b32 v56, v179, v26
	s_waitcnt lgkmcnt(0)
	v_add_f32_e32 v26, v26, v56
	ds_bpermute_b32 v56, v180, v26
	s_waitcnt lgkmcnt(0)
	v_add_f32_e32 v26, v26, v56
	ds_bpermute_b32 v56, v187, v26
	s_waitcnt lgkmcnt(0)
; __global__ void __launch_bounds__(NTHR) mega_fwd(Params p) {
;     ...
; #pragma unroll
;                       for (int r = 0; r < 16; ++r) { float q = ss[r]; q += __shfl_xor(q, 1); q += __shfl_xor(q, 2); q += __shfl_xor(q, 4); q += __shfl_xor(q, 8); q += __shfl_xor(q, 16);
;                           const float rstd = 1.0f / sqrtf(q * (1.0f / 128.0f) + EPS);
; #pragma unroll
;                           for (int d = 0; d < 4; ++d) o[d][r] *= rstd * gsub[d]; } }
	v_add_f32_e32 v26, v26, v56
	v_fmamk_f32 v26, v26, 0x3c000000, v189
	v_cmp_gt_f32_e32 vcc, s2, v26
	v_mul_f32_e32 v56, 0x4f800000, v26
	s_nop 0
	v_cndmask_b32_e32 v26, v26, v56, vcc
	v_sqrt_f32_e32 v56, v26
	s_nop 0
	v_add_u32_e32 v66, -1, v56
	v_fma_f32 v75, -v66, v56, v26
	v_cmp_ge_f32_e64 s[0:1], 0, v75
	v_add_u32_e32 v75, 1, v56
	s_nop 0
	v_cndmask_b32_e64 v66, v56, v66, s[0:1]
	v_fma_f32 v56, -v75, v56, v26
	v_cmp_lt_f32_e64 s[0:1], 0, v56
	s_nop 1
	v_cndmask_b32_e64 v56, v66, v75, s[0:1]
	v_mul_f32_e32 v66, 0x37800000, v56
	v_cndmask_b32_e32 v56, v56, v66, vcc
	v_cmp_class_f32_e32 vcc, v26, v190
	s_nop 1
	v_cndmask_b32_e32 v26, v56, v26, vcc
	v_div_scale_f32 v56, s[0:1], v26, v26, 1.0
	v_rcp_f32_e32 v66, v56
	s_nop 0
	v_fma_f32 v75, -v56, v66, 1.0
	v_fmac_f32_e32 v66, v75, v66
	v_div_scale_f32 v75, vcc, 1.0, v26, 1.0
	v_mul_f32_e32 v77, v75, v66
	v_fma_f32 v78, -v56, v77, v75
	v_fmac_f32_e32 v77, v78, v66
	v_fma_f32 v56, -v56, v77, v75
	v_div_fmas_f32 v56, v56, v66, v77
	v_div_fixup_f32 v56, v56, v26, 1.0
	v_mul_f32_e32 v26, v56, v0
	v_mul_f32_e32 v19, v26, v19
	v_mul_f32_e32 v26, v56, v4
	v_mul_f32_e32 v26, v26, v30
	v_mul_f32_e32 v30, v56, v5
	v_mul_f32_e32 v30, v30, v43
	v_mul_f32_e32 v43, v56, v6
	v_mul_f32_e32 v43, v43, v46
	ds_bpermute_b32 v46, v162, v27
	s_waitcnt lgkmcnt(0)
	v_add_f32_e32 v27, v27, v46
	ds_bpermute_b32 v46, v178, v27
	s_waitcnt lgkmcnt(0)
	v_add_f32_e32 v27, v27, v46
	ds_bpermute_b32 v46, v179, v27
	s_waitcnt lgkmcnt(0)
	v_add_f32_e32 v27, v27, v46
	ds_bpermute_b32 v46, v180, v27
	s_waitcnt lgkmcnt(0)
	v_add_f32_e32 v27, v27, v46
	ds_bpermute_b32 v46, v187, v27
	s_waitcnt lgkmcnt(0)
	v_add_f32_e32 v27, v27, v46
	v_fmamk_f32 v27, v27, 0x3c000000, v189
	v_cmp_gt_f32_e32 vcc, s2, v27
	v_mul_f32_e32 v46, 0x4f800000, v27
	s_nop 0
	v_cndmask_b32_e32 v27, v27, v46, vcc
	v_sqrt_f32_e32 v46, v27
	s_nop 0
	v_add_u32_e32 v56, -1, v46
	v_fma_f32 v66, -v56, v46, v27
	v_cmp_ge_f32_e64 s[0:1], 0, v66
	v_add_u32_e32 v66, 1, v46
	s_nop 0
	v_cndmask_b32_e64 v56, v46, v56, s[0:1]
	v_fma_f32 v46, -v66, v46, v27
	v_cmp_lt_f32_e64 s[0:1], 0, v46
	s_nop 1
	v_cndmask_b32_e64 v46, v56, v66, s[0:1]
	v_mul_f32_e32 v56, 0x37800000, v46
	v_cndmask_b32_e32 v46, v46, v56, vcc
	v_cmp_class_f32_e32 vcc, v27, v190
	s_nop 1
	v_cndmask_b32_e32 v27, v46, v27, vcc
	v_div_scale_f32 v46, s[0:1], v27, v27, 1.0
	v_rcp_f32_e32 v56, v46
	s_nop 0
	v_fma_f32 v66, -v46, v56, 1.0
	v_fmac_f32_e32 v56, v66, v56
	v_div_scale_f32 v66, vcc, 1.0, v27, 1.0
	v_mul_f32_e32 v75, v66, v56
	v_fma_f32 v77, -v46, v75, v66
	v_fmac_f32_e32 v75, v77, v56
	v_fma_f32 v46, -v46, v75, v66
	v_div_fmas_f32 v46, v46, v56, v75
	v_div_fixup_f32 v46, v46, v27, 1.0
	v_mul_f32_e32 v27, v46, v0
	v_mul_f32_e32 v15, v27, v15
	v_mul_f32_e32 v27, v46, v4
	v_mul_f32_e32 v21, v27, v21
	v_mul_f32_e32 v27, v46, v5
	v_mul_f32_e32 v27, v27, v35
	v_mul_f32_e32 v35, v46, v6
	v_mul_f32_e32 v35, v35, v36
	ds_bpermute_b32 v36, v162, v12
	s_waitcnt lgkmcnt(0)
	v_add_f32_e32 v12, v12, v36
	ds_bpermute_b32 v36, v178, v12
	s_waitcnt lgkmcnt(0)
	v_add_f32_e32 v12, v12, v36
	ds_bpermute_b32 v36, v179, v12
	s_waitcnt lgkmcnt(0)
	v_add_f32_e32 v12, v12, v36
	ds_bpermute_b32 v36, v180, v12
	s_waitcnt lgkmcnt(0)
	v_add_f32_e32 v12, v12, v36
	ds_bpermute_b32 v36, v187, v12
	s_waitcnt lgkmcnt(0)
	v_add_f32_e32 v12, v12, v36
	v_fmamk_f32 v12, v12, 0x3c000000, v189
	v_cmp_gt_f32_e32 vcc, s2, v12
	v_mul_f32_e32 v36, 0x4f800000, v12
	s_nop 0
	v_cndmask_b32_e32 v12, v12, v36, vcc
	v_sqrt_f32_e32 v36, v12
	s_nop 0
	v_add_u32_e32 v46, -1, v36
	v_fma_f32 v56, -v46, v36, v12
	v_cmp_ge_f32_e64 s[0:1], 0, v56
	v_add_u32_e32 v56, 1, v36
	s_nop 0
	v_cndmask_b32_e64 v46, v36, v46, s[0:1]
	v_fma_f32 v36, -v56, v36, v12
	v_cmp_lt_f32_e64 s[0:1], 0, v36
	s_nop 1
	v_cndmask_b32_e64 v36, v46, v56, s[0:1]
	v_mul_f32_e32 v46, 0x37800000, v36
	v_cndmask_b32_e32 v36, v36, v46, vcc
	v_cmp_class_f32_e32 vcc, v12, v190
	s_nop 1
	v_cndmask_b32_e32 v12, v36, v12, vcc
	v_div_scale_f32 v36, s[0:1], v12, v12, 1.0
	v_rcp_f32_e32 v46, v36
	s_nop 0
	v_fma_f32 v56, -v36, v46, 1.0
	v_fmac_f32_e32 v46, v56, v46
	v_div_scale_f32 v56, vcc, 1.0, v12, 1.0
	v_mul_f32_e32 v66, v56, v46
	v_fma_f32 v75, -v36, v66, v56
	v_fmac_f32_e32 v66, v75, v46
	v_fma_f32 v36, -v36, v66, v56
	v_div_fmas_f32 v36, v36, v46, v66
	v_div_fixup_f32 v36, v36, v12, 1.0
	v_mul_f32_e32 v12, v36, v0
	v_mul_f32_e32 v9, v12, v9
	v_mul_f32_e32 v12, v36, v4
	v_mul_f32_e32 v12, v12, v16
	v_mul_f32_e32 v16, v36, v5
	v_mul_f32_e32 v16, v16, v25
	v_mul_f32_e32 v25, v36, v6
	v_mul_f32_e32 v25, v25, v28
	ds_bpermute_b32 v28, v162, v13
	s_waitcnt lgkmcnt(0)
	v_add_f32_e32 v13, v13, v28
	ds_bpermute_b32 v28, v178, v13
	s_waitcnt lgkmcnt(0)
	v_add_f32_e32 v13, v13, v28
	ds_bpermute_b32 v28, v179, v13
	s_waitcnt lgkmcnt(0)
	v_add_f32_e32 v13, v13, v28
	ds_bpermute_b32 v28, v180, v13
	s_waitcnt lgkmcnt(0)
	v_add_f32_e32 v13, v13, v28
	ds_bpermute_b32 v28, v187, v13
	s_waitcnt lgkmcnt(0)
	v_add_f32_e32 v13, v13, v28
	v_fmamk_f32 v13, v13, 0x3c000000, v189
	v_cmp_gt_f32_e32 vcc, s2, v13
	v_mul_f32_e32 v28, 0x4f800000, v13
	s_nop 0
	v_cndmask_b32_e32 v13, v13, v28, vcc
	v_sqrt_f32_e32 v28, v13
	s_nop 0
	v_add_u32_e32 v36, -1, v28
	v_fma_f32 v46, -v36, v28, v13
	v_cmp_ge_f32_e64 s[0:1], 0, v46
	v_add_u32_e32 v46, 1, v28
	s_nop 0
	v_cndmask_b32_e64 v36, v28, v36, s[0:1]
	v_fma_f32 v28, -v46, v28, v13
	v_cmp_lt_f32_e64 s[0:1], 0, v28
	s_nop 1
	v_cndmask_b32_e64 v28, v36, v46, s[0:1]
	v_mul_f32_e32 v36, 0x37800000, v28
	v_cndmask_b32_e32 v28, v28, v36, vcc
	v_cmp_class_f32_e32 vcc, v13, v190
	s_nop 1
	v_cndmask_b32_e32 v13, v28, v13, vcc
	v_div_scale_f32 v28, s[0:1], v13, v13, 1.0
	v_rcp_f32_e32 v36, v28
	s_nop 0
	v_fma_f32 v46, -v28, v36, 1.0
	v_fmac_f32_e32 v36, v46, v36
	v_div_scale_f32 v46, vcc, 1.0, v13, 1.0
	v_mul_f32_e32 v56, v46, v36
	v_fma_f32 v66, -v28, v56, v46
	v_fmac_f32_e32 v56, v66, v36
	v_fma_f32 v28, -v28, v56, v46
	v_div_fmas_f32 v28, v28, v36, v56
	v_div_fixup_f32 v13, v28, v13, 1.0
	v_mul_f32_e32 v28, v13, v0
	v_mul_f32_e32 v7, v28, v7
	v_mul_f32_e32 v28, v13, v4
	v_mul_f32_e32 v11, v28, v11
	v_mul_f32_e32 v28, v13, v5
	v_mul_f32_e32 v13, v13, v6
	v_mul_f32_e32 v13, v13, v18
	ds_bpermute_b32 v18, v162, v3
	v_mul_f32_e32 v17, v28, v17
	s_waitcnt lgkmcnt(0)
; __device__ __forceinline__ int opaque_tid() { int t = threadIdx.x; asm volatile("" : "+v"(t)); return t; }
; __device__ __forceinline__ void store_o_bf16(const att::f32x16 (&o)[4], bf16* base  , unsigned char* lds) {
;     const int tid = opaque_tid(), lane = tid & 63, wave = __builtin_amdgcn_readfirstlane(tid >> 6), r32 = lane & 31, hi = lane >> 5;
;     __syncthreads();
;     float* T = (float*)(lds + wave * 16896);
; __global__ void __launch_bounds__(NTHR) mega_fwd(Params p) {
;     ...
;                       for (int r = 0; r < 16; ++r) { float q = ss[r]; q += __shfl_xor(q, 1); q += __shfl_xor(q, 2); q += __shfl_xor(q, 4); q += __shfl_xor(q, 8); q += __shfl_xor(q, 16);
;                           const float rstd = 1.0f / sqrtf(q * (1.0f / 128.0f) + EPS);
; #pragma unroll
;                           for (int d = 0; d < 4; ++d) o[d][r] *= rstd * gsub[d]; } }
	v_add_f32_e32 v3, v3, v18
	ds_bpermute_b32 v18, v178, v3
	s_waitcnt lgkmcnt(0)
	v_add_f32_e32 v3, v3, v18
	ds_bpermute_b32 v18, v179, v3
	s_waitcnt lgkmcnt(0)
	v_add_f32_e32 v3, v3, v18
	ds_bpermute_b32 v18, v180, v3
	s_waitcnt lgkmcnt(0)
	v_add_f32_e32 v3, v3, v18
	ds_bpermute_b32 v18, v187, v3
	s_waitcnt lgkmcnt(0)
	v_add_f32_e32 v3, v3, v18
	v_fmamk_f32 v3, v3, 0x3c000000, v189
	v_cmp_gt_f32_e32 vcc, s2, v3
	v_mul_f32_e32 v18, 0x4f800000, v3
	v_readlane_b32 s2, v253, 7
	v_cndmask_b32_e32 v3, v3, v18, vcc
	v_sqrt_f32_e32 v18, v3
	v_readlane_b32 s3, v253, 8
	v_add_u32_e32 v28, -1, v18
	v_fma_f32 v36, -v28, v18, v3
	v_cmp_ge_f32_e64 s[0:1], 0, v36
	v_add_u32_e32 v36, 1, v18
	s_nop 0
	v_cndmask_b32_e64 v28, v18, v28, s[0:1]
	v_fma_f32 v18, -v36, v18, v3
	v_cmp_lt_f32_e64 s[0:1], 0, v18
	s_nop 1
	v_cndmask_b32_e64 v18, v28, v36, s[0:1]
	v_mul_f32_e32 v28, 0x37800000, v18
	v_cndmask_b32_e32 v18, v18, v28, vcc
	v_cmp_class_f32_e32 vcc, v3, v190
	s_nop 1
	v_cndmask_b32_e32 v3, v18, v3, vcc
	v_div_scale_f32 v18, s[0:1], v3, v3, 1.0
	v_rcp_f32_e32 v28, v18
	s_nop 0
	v_fma_f32 v36, -v18, v28, 1.0
	v_fmac_f32_e32 v28, v36, v28
	v_div_scale_f32 v36, vcc, 1.0, v3, 1.0
	v_mul_f32_e32 v46, v36, v28
	v_fma_f32 v56, -v18, v46, v36
	v_fmac_f32_e32 v46, v56, v28
	v_fma_f32 v18, -v18, v46, v36
	v_div_fmas_f32 v18, v18, v28, v46
	v_div_fixup_f32 v3, v18, v3, 1.0
	v_mul_f32_e32 v0, v3, v0
	v_mul_f32_e32 v0, v0, v2
	v_mul_f32_e32 v2, v3, v4
	v_mul_f32_e32 v4, v3, v5
	v_mov_b32_e32 v5, v188
	v_mul_f32_e32 v2, v2, v8
	v_readfirstlane_b32 s0, v5
	s_ashr_i32 s0, s0, 6
	v_lshrrev_b32_e32 v8, 3, v5
	v_mul_f32_e32 v3, v3, v6
	v_and_b32_e32 v6, 31, v5
	s_mul_i32 s1, s0, 0x4200
	v_and_b32_e32 v8, 4, v8
	s_add_i32 s1, s1, 0
	v_lshlrev_b32_e32 v6, 2, v6
	v_mul_u32_u24_e32 v8, 0x210, v8
	v_add3_u32 v6, s1, v6, v8
	v_add_u32_e32 v8, 0x400, v6
	s_barrier
; __device__ __forceinline__ int crow(int r, int hi) { return (r & 3) + 8 * (r >> 2) + 4 * hi; }
; __device__ __forceinline__ unsigned cvtpk(float lo, float hi) { unsigned r; asm volatile("v_cvt_pk_bf16_f32 %0, %1, %2" : "=v"(r) : "v"(lo), "v"(hi)); return r; }
; __device__ __forceinline__ void store_o_bf16(const att::f32x16 (&o)[4], bf16* base  , unsigned char* lds) {
;     ...
; #pragma unroll
;     for (int r = 0; r < 16; ++r) { float* tp = T + att::crow(r, hi) * 132 + r32;
; #pragma unroll
;         for (int d = 0; d < 4; ++d) tp[32 * d] = o[d][r]; }
; #pragma unroll
;     for (int k = 0; k < 8; ++k) { const int chunk = k * 64 + lane, row = chunk >> 4, c8 = chunk & 15;
;         const f32x4 a = *(const f32x4*)(T + row * 132 + c8 * 8), b = *(const f32x4*)(T + row * 132 + c8 * 8 + 4);
;         v4u w; w.x = att::cvtpk(a.x, a.y); w.y = att::cvtpk(a.z, a.w); w.z = att::cvtpk(b.x, b.y); w.w = att::cvtpk(b.z, b.w);
;         *(v4u*)(base + (size_t)(wave * 32 + row) * DM + c8 * 8) = w; }
; }
	ds_write2_b32 v6, v20, v22 offset1:32
	ds_write2_b32 v6, v23, v24 offset0:64 offset1:96
	ds_write2_b32 v6, v31, v32 offset0:132 offset1:164
	ds_write2_b32 v6, v33, v34 offset0:196 offset1:228
	ds_write2_b32 v8, v39, v40 offset0:8 offset1:40
	ds_write2_b32 v8, v41, v42 offset0:72 offset1:104
	ds_write2_b32 v8, v49, v50 offset0:140 offset1:172
	ds_write2_b32 v8, v51, v52 offset0:204 offset1:236
	v_add_u32_e32 v8, 0x1000, v6
	ds_write2_b32 v8, v58, v59 offset0:32 offset1:64
	ds_write2_b32 v8, v60, v61 offset0:96 offset1:128
	ds_write2_b32 v8, v67, v68 offset0:164 offset1:196
	v_add_u32_e32 v8, 0x1200, v6
	ds_write2_b32 v8, v69, v70 offset0:100 offset1:132
	v_add_u32_e32 v8, 0x1400, v6
	ds_write2_b32 v8, v64, v72 offset0:40 offset1:72
	ds_write2_b32 v8, v74, v76 offset0:104 offset1:136
	ds_write2_b32 v8, v54, v55 offset0:172 offset1:204
	v_add_u32_e32 v8, 0x1600, v6
	ds_write2_b32 v8, v63, v73 offset0:108 offset1:140
	v_add_u32_e32 v8, 0x2000, v6
	ds_write2_b32 v8, v47, v57 offset0:64 offset1:96
	ds_write2_b32 v8, v65, v71 offset0:128 offset1:160
	ds_write2_b32 v8, v37, v44 offset0:196 offset1:228
	v_add_u32_e32 v8, 0x2400, v6
	ds_write2_b32 v8, v48, v62 offset0:4 offset1:36
	ds_write2_b32 v8, v29, v38 offset0:72 offset1:104
	ds_write2_b32 v8, v45, v53 offset0:136 offset1:168
	ds_write2_b32 v8, v19, v26 offset0:204 offset1:236
	v_add_u32_e32 v8, 0x2800, v6
	ds_write2_b32 v8, v30, v43 offset0:12 offset1:44
	v_add_u32_e32 v8, 0x3000, v6
	ds_write2_b32 v8, v15, v21 offset0:96 offset1:128
	ds_write2_b32 v8, v27, v35 offset0:160 offset1:192
	v_add_u32_e32 v8, 0x3200, v6
	ds_write2_b32 v8, v9, v12 offset0:100 offset1:132
	v_add_u32_e32 v8, 0x3400, v6
	ds_write2_b32 v8, v16, v25 offset0:36 offset1:68
	ds_write2_b32 v8, v7, v11 offset0:104 offset1:136
	ds_write2_b32 v8, v17, v13 offset0:168 offset1:200
	v_add_u32_e32 v7, 0x3600, v6
	v_mul_f32_e32 v4, v4, v10
	v_mul_f32_e32 v3, v3, v14
	ds_write2_b32 v7, v0, v2 offset0:108 offset1:140
	v_add_u32_e32 v0, 0x3800, v6
	ds_write2_b32 v0, v4, v3 offset0:44 offset1:76
	v_lshlrev_b32_e32 v0, 3, v5
	v_and_b32_e32 v0, 0x78, v0
	v_lshlrev_b32_e32 v2, 2, v0
	v_lshlrev_b32_e32 v0, 1, v0
	v_lshl_add_u64 v[6:7], s[2:3], 0, v[0:1]
	v_bfe_u32 v0, v5, 4, 2
	v_mul_u32_u24_e32 v3, 0x210, v0
	v_add3_u32 v14, s1, v2, v3
	ds_read_b128 v[2:5], v14
	ds_read_b128 v[8:11], v14 offset:16
	s_waitcnt lgkmcnt(1)
	v_cvt_pk_bf16_f32 v2, v2, v3
	v_cvt_pk_bf16_f32 v3, v4, v5
	s_waitcnt lgkmcnt(0)
	v_cvt_pk_bf16_f32 v4, v8, v9
	v_lshl_or_b32 v8, s0, 5, v0
	v_ashrrev_i32_e32 v9, 31, v8
	v_cvt_pk_bf16_f32 v5, v10, v11
	v_lshlrev_b64 v[10:11], 12, v[8:9]
	v_lshl_add_u64 v[10:11], v[6:7], 0, v[10:11]
	global_store_dwordx4 v[10:11], v[2:5], off
	ds_read_b128 v[2:5], v14 offset:2112
	ds_read_b128 v[10:13], v14 offset:2128
	s_waitcnt lgkmcnt(1)
	v_cvt_pk_bf16_f32 v2, v2, v3
	v_cvt_pk_bf16_f32 v3, v4, v5
	s_waitcnt lgkmcnt(0)
	v_cvt_pk_bf16_f32 v4, v10, v11
	v_or_b32_e32 v10, 4, v8
	v_ashrrev_i32_e32 v11, 31, v10
	v_lshlrev_b64 v[10:11], 12, v[10:11]
	v_lshl_add_u64 v[10:11], v[6:7], 0, v[10:11]
	v_cvt_pk_bf16_f32 v5, v12, v13
	global_store_dwordx4 v[10:11], v[2:5], off
	ds_read_b128 v[2:5], v14 offset:4224
	ds_read_b128 v[10:13], v14 offset:4240
	s_waitcnt lgkmcnt(1)
	v_cvt_pk_bf16_f32 v2, v2, v3
	v_cvt_pk_bf16_f32 v3, v4, v5
	s_waitcnt lgkmcnt(0)
	v_cvt_pk_bf16_f32 v4, v10, v11
	v_or_b32_e32 v10, 8, v8
	v_ashrrev_i32_e32 v11, 31, v10
	v_lshlrev_b64 v[10:11], 12, v[10:11]
	v_lshl_add_u64 v[10:11], v[6:7], 0, v[10:11]
	v_cvt_pk_bf16_f32 v5, v12, v13
	global_store_dwordx4 v[10:11], v[2:5], off
	ds_read_b128 v[2:5], v14 offset:6336
	ds_read_b128 v[10:13], v14 offset:6352
	s_waitcnt lgkmcnt(1)
	v_cvt_pk_bf16_f32 v2, v2, v3
	v_cvt_pk_bf16_f32 v3, v4, v5
	s_waitcnt lgkmcnt(0)
	v_cvt_pk_bf16_f32 v4, v10, v11
	v_or_b32_e32 v10, 12, v8
	v_ashrrev_i32_e32 v11, 31, v10
	v_lshlrev_b64 v[10:11], 12, v[10:11]
	v_lshl_add_u64 v[10:11], v[6:7], 0, v[10:11]
	v_cvt_pk_bf16_f32 v5, v12, v13
	global_store_dwordx4 v[10:11], v[2:5], off
	ds_read_b128 v[2:5], v14 offset:8448
	ds_read_b128 v[10:13], v14 offset:8464
	s_waitcnt lgkmcnt(1)
	v_cvt_pk_bf16_f32 v2, v2, v3
	v_cvt_pk_bf16_f32 v3, v4, v5
	s_waitcnt lgkmcnt(0)
	v_cvt_pk_bf16_f32 v4, v10, v11
	v_or_b32_e32 v10, 16, v8
	v_ashrrev_i32_e32 v11, 31, v10
	v_lshlrev_b64 v[10:11], 12, v[10:11]
	v_lshl_add_u64 v[10:11], v[6:7], 0, v[10:11]
	v_cvt_pk_bf16_f32 v5, v12, v13
	global_store_dwordx4 v[10:11], v[2:5], off
	ds_read_b128 v[2:5], v14 offset:10560
	ds_read_b128 v[10:13], v14 offset:10576
	s_waitcnt lgkmcnt(1)
	v_cvt_pk_bf16_f32 v2, v2, v3
	v_cvt_pk_bf16_f32 v3, v4, v5
	s_waitcnt lgkmcnt(0)
	v_cvt_pk_bf16_f32 v4, v10, v11
	v_or_b32_e32 v10, 20, v8
	v_ashrrev_i32_e32 v11, 31, v10
	v_lshlrev_b64 v[10:11], 12, v[10:11]
	v_lshl_add_u64 v[10:11], v[6:7], 0, v[10:11]
	v_cvt_pk_bf16_f32 v5, v12, v13
	global_store_dwordx4 v[10:11], v[2:5], off
	ds_read_b128 v[2:5], v14 offset:12672
	ds_read_b128 v[10:13], v14 offset:12688
	s_waitcnt lgkmcnt(1)
	v_cvt_pk_bf16_f32 v2, v2, v3
	v_cvt_pk_bf16_f32 v3, v4, v5
	s_waitcnt lgkmcnt(0)
	v_cvt_pk_bf16_f32 v4, v10, v11
	v_or_b32_e32 v10, 24, v8
	v_ashrrev_i32_e32 v11, 31, v10
	v_lshlrev_b64 v[10:11], 12, v[10:11]
	v_lshl_add_u64 v[10:11], v[6:7], 0, v[10:11]
	v_cvt_pk_bf16_f32 v5, v12, v13
	global_store_dwordx4 v[10:11], v[2:5], off
	ds_read_b128 v[2:5], v14 offset:14784
	ds_read_b128 v[10:13], v14 offset:14800
	v_or_b32_e32 v8, 28, v8
	s_waitcnt lgkmcnt(1)
	v_cvt_pk_bf16_f32 v2, v2, v3
	v_cvt_pk_bf16_f32 v3, v4, v5
	s_waitcnt lgkmcnt(0)
	v_cvt_pk_bf16_f32 v4, v10, v11
	v_cvt_pk_bf16_f32 v5, v12, v13

; #define SBAR() __builtin_amdgcn_sched_barrier(0)
; #define SLOAD(i, k0) do { sr_[i].vs0 = *reinterpret_cast<const bf16x8*>(&Vh[(long)((k0) + sr) * LDP + sc]); sr_[i].vs1 = *reinterpret_cast<const bf16x8*>(&Vh[(long)((k0) + 32 + sr) * LDP + sc]); \
;     sr_[i].ks0 = *reinterpret_cast<const bf16x8*>(&Kh[(long)((k0) + ksr) * LDP + ksc]); if (DK == 128) sr_[i].ks1 = *reinterpret_cast<const bf16x8*>(&Kh[(long)((k0) + 32 + ksr) * LDP + ksc]); } while (0)
; #define HOOK(P0, P1, j) do { if (NA) na_hook(P0, P1, krow0 + (j), q_row, q_col, win_r, win_c, rpb, inv_scale, hi); } while (0)
; template <int DK, bool QL>
; __device__ __forceinline__ void qkt(f32x16& p0, f32x16& p1, const bf16* Ks, const bf16x8* qr, const char* ql, int r32, int hi) {
;   p0 = f32x16{}; p1 = f32x16{};
; #pragma unroll
;   for (int d0 = 0; d0 < DK / 16; ++d0) { int cb = (d0 * 16 + hi * 8) * 2;
;     const bf16x8 qv = QL ? *reinterpret_cast<const bf16x8*>(ql + d0 * 1024) : qr[d0];
;     bf16x8 b0 = *reinterpret_cast<const bf16x8*>((const char*)Ks + kswz<DK>(r32, cb));
;     bf16x8 b1 = *reinterpret_cast<const bf16x8*>((const char*)Ks + kswz<DK>(32 + r32, cb));
;     p0 = __builtin_amdgcn_mfma_f32_32x32x16_bf16(b0, qv, p0, 0, 0, 0);
;     p1 = __builtin_amdgcn_mfma_f32_32x32x16_bf16(b1, qv, p1, 0, 0, 0); }
; template <int DK, bool NA, bool QL, int SD> ...
;     ...
;     SBAR(); qkt<DK, QL>(pB0, pB1, (bf16*)((char*)K_lds + SHM_K), qr, ql, r32, hi); HOOK(pB0, pB1, j);
;     finishSM(pA0, pA1, alA, l_reg, pa0, pa1, pa2, pa3); SBAR();
;     SLOAD(SO, (j + SD) * KVBLK); SBAR();
;     pv_d0(o, vb0, pa0, pa1, pa2, pa3); partialSM(pB0, pB1, m_reg, mnB, alB, C, thrRaw);
.LBB0_682:
	ds_read_b128 v[66:69], v212 offset:49152
	ds_read_b128 v[70:73], v212 offset:53248
	ds_read_b128 v[182:185], v217 offset:49152
	ds_read_b128 v[190:193], v217 offset:53248
	ds_read_b128 v[168:171], v218 offset:49152
	ds_read_b128 v[194:197], v218 offset:53248
	v_exp_f32_e32 v143, v138
	v_add_f32_e32 v138, 0, v177
	v_add_f32_e32 v138, v226, v138
	s_waitcnt lgkmcnt(5)
	v_mfma_f32_32x32x16_bf16 v[82:97], v[66:69], v[110:113], 0
	v_add_f32_e32 v138, v161, v138
	v_add_f32_e32 v138, v223, v138
	v_add_f32_e32 v138, v153, v138
	ds_read_b128 v[228:231], v216 offset:49152
	ds_read_b128 v[232:235], v216 offset:53248
	v_add_f32_e32 v138, v176, v138
	v_add_f32_e32 v138, v152, v138
	v_add_f32_e32 v138, v160, v138
	s_waitcnt lgkmcnt(6)
	v_mfma_f32_32x32x16_bf16 v[66:81], v[70:73], v[110:113], 0
	v_add_f32_e32 v138, v149, v138
	v_add_f32_e32 v138, v151, v138
	v_add_f32_e32 v138, v147, v138
	v_add_f32_e32 v138, v150, v138
	v_add_f32_e32 v138, v145, v138
	v_exp_f32_e32 v164, v139
	v_add_f32_e32 v138, v148, v138
	s_waitcnt lgkmcnt(1)
	v_mfma_f32_32x32x16_bf16 v[82:97], v[228:231], v[106:109], v[82:97]
	v_exp_f32_e32 v136, v136
	v_add_f32_e32 v138, v144, v138
	v_exp_f32_e32 v137, v137
	v_add_f32_e32 v138, v146, v138
	v_exp_f32_e32 v130, v130
	v_add_f32_e32 v138, v143, v138
	v_exp_f32_e32 v131, v131
	s_waitcnt lgkmcnt(0)
	v_mfma_f32_32x32x16_bf16 v[66:81], v[232:235], v[106:109], v[66:81]
	v_add_f32_e32 v138, v164, v138
	v_exp_f32_e32 v128, v128
	v_add_f32_e32 v138, v136, v138
	v_exp_f32_e32 v129, v129
	v_add_f32_e32 v138, v137, v138
	v_exp_f32_e32 v126, v126
	s_waitcnt lgkmcnt(0)
	v_mfma_f32_32x32x16_bf16 v[82:97], v[182:185], v[98:101], v[82:97]
	v_add_f32_e32 v138, v130, v138
	v_exp_f32_e32 v127, v127
	v_add_f32_e32 v138, v131, v138
	v_exp_f32_e32 v165, v140
	v_add_f32_e32 v138, v128, v138
	v_exp_f32_e32 v166, v141
	v_add_f32_e32 v138, v129, v138
	s_waitcnt lgkmcnt(0)
	v_mfma_f32_32x32x16_bf16 v[66:81], v[190:193], v[98:101], v[66:81]
	v_exp_f32_e32 v134, v134
	v_add_f32_e32 v138, v126, v138
	v_exp_f32_e32 v135, v135
	v_add_f32_e32 v138, v127, v138
	v_exp_f32_e32 v132, v132
	v_add_f32_e32 v138, v165, v138
	s_waitcnt lgkmcnt(0)
	v_mfma_f32_32x32x16_bf16 v[82:97], v[168:171], v[102:105], v[82:97]
	v_exp_f32_e32 v133, v133
	v_add_f32_e32 v138, v166, v138
	v_add_f32_e32 v138, v134, v138
	v_add_f32_e32 v138, v135, v138
	v_add_f32_e32 v138, v132, v138
	v_add_f32_e32 v220, v133, v138
	v_mov_b32_e32 v221, v220
	s_waitcnt lgkmcnt(0)
	v_mfma_f32_32x32x16_bf16 v[66:81], v[194:197], v[102:105], v[66:81]
	v_cvt_pk_bf16_f32 v138, v177, v226
	v_cvt_pk_bf16_f32 v139, v161, v223
	v_cvt_pk_bf16_f32 v140, v153, v176
	v_cvt_pk_bf16_f32 v141, v152, v160
	v_cvt_pk_bf16_f32 v222, v149, v151
	v_cvt_pk_bf16_f32 v223, v147, v150
	v_cvt_pk_bf16_f32 v224, v145, v148
	v_permlane32_swap_b32_e32 v220, v221
	v_permlane32_swap_b32_e32 v138, v140
	v_cvt_pk_bf16_f32 v225, v144, v146
	v_permlane32_swap_b32_e32 v222, v224
	v_cvt_pk_bf16_f32 v144, v143, v164
	v_cvt_pk_bf16_f32 v145, v136, v137
	v_cvt_pk_bf16_f32 v146, v130, v131
	v_cvt_pk_bf16_f32 v147, v128, v129
	v_cvt_pk_bf16_f32 v148, v126, v127
	v_cvt_pk_bf16_f32 v149, v165, v166
	v_cvt_pk_bf16_f32 v150, v134, v135
	v_cvt_pk_bf16_f32 v151, v132, v133
	v_permlane32_swap_b32_e32 v139, v141
	v_permlane32_swap_b32_e32 v223, v225
	v_permlane32_swap_b32_e32 v144, v146
	v_permlane32_swap_b32_e32 v145, v147
	v_permlane32_swap_b32_e32 v148, v150
	v_permlane32_swap_b32_e32 v149, v151
	v_readlane_b32 s2, v254, 32
	v_readlane_b32 s3, v254, 33
	s_mov_b32 s4, 0xe0e0000
	s_mov_b32 s5, 0xe130000
	v_lshl_add_u64 v[160:161], v[156:157], 0, s[2:3]
	v_add_co_u32_e32 v126, vcc, s4, v160
	v_lshl_add_u64 v[176:177], v[158:159], 0, s[2:3]
	s_nop 0
	v_addc_co_u32_e32 v127, vcc, 0, v161, vcc
	v_add_co_u32_e32 v130, vcc, s5, v160
	s_nop 1
	v_addc_co_u32_e32 v131, vcc, 0, v161, vcc
	v_add_co_u32_e32 v134, vcc, s4, v176
	global_load_dwordx4 v[126:129], v[126:127], off offset:2048
	s_nop 0
	global_load_dwordx4 v[130:133], v[130:131], off offset:2048
	v_addc_co_u32_e32 v135, vcc, 0, v177, vcc
	global_load_dwordx4 v[134:137], v[134:135], off offset:1024
	ds_read_b64_tr_b16 v[226:227], v211 offset:0
	ds_read_b64_tr_b16 v[228:229], v211 offset:0x800
	ds_read_b64_tr_b16 v[230:231], v211 offset:0x1000
	ds_read_b64_tr_b16 v[232:233], v211 offset:0x1800
	ds_read_b64_tr_b16 v[234:235], v211 offset:0x2000
	ds_read_b64_tr_b16 v[236:237], v211 offset:0x2800
	ds_read_b64_tr_b16 v[238:239], v211 offset:0x3000
	ds_read_b64_tr_b16 v[240:241], v211 offset:0x3800
	s_waitcnt lgkmcnt(0)
	s_nop 0
	v_mfma_f32_32x32x16_bf16 v[18:33], v[138:141], v[226:229], v[18:33]
	ds_read_b64_tr_b16 v[226:227], v211 offset:0x200
	ds_read_b64_tr_b16 v[228:229], v211 offset:0xa00
	v_mfma_f32_32x32x16_bf16 v[18:33], v[222:225], v[230:233], v[18:33]
	ds_read_b64_tr_b16 v[230:231], v211 offset:0x1200
	ds_read_b64_tr_b16 v[232:233], v211 offset:0x1a00
	v_mfma_f32_32x32x16_bf16 v[18:33], v[144:147], v[234:237], v[18:33]
	ds_read_b64_tr_b16 v[234:235], v211 offset:0x2200
	ds_read_b64_tr_b16 v[236:237], v211 offset:0x2a00
	v_mfma_f32_32x32x16_bf16 v[18:33], v[148:151], v[238:241], v[18:33]
	ds_read_b64_tr_b16 v[238:239], v211 offset:0x3200
	ds_read_b64_tr_b16 v[240:241], v211 offset:0x3a00
	s_waitcnt lgkmcnt(0)
	v_mfma_f32_32x32x16_bf16 v[2:17], v[138:141], v[226:229], v[2:17]
	ds_read_b64_tr_b16 v[226:227], v211 offset:0x400
	ds_read_b64_tr_b16 v[228:229], v211 offset:0xc00
	v_mfma_f32_32x32x16_bf16 v[2:17], v[222:225], v[230:233], v[2:17]
	ds_read_b64_tr_b16 v[230:231], v211 offset:0x1400
	ds_read_b64_tr_b16 v[232:233], v211 offset:0x1c00
	v_mfma_f32_32x32x16_bf16 v[2:17], v[144:147], v[234:237], v[2:17]
	ds_read_b64_tr_b16 v[234:235], v211 offset:0x2400
	ds_read_b64_tr_b16 v[236:237], v211 offset:0x2c00
	v_mfma_f32_32x32x16_bf16 v[2:17], v[148:151], v[238:241], v[2:17]
	ds_read_b64_tr_b16 v[238:239], v211 offset:0x3400
	ds_read_b64_tr_b16 v[240:241], v211 offset:0x3c00
	s_waitcnt lgkmcnt(0)
; #define SWAIT() do { if (SD == 1) asm volatile("s_waitcnt vmcnt(0)" ::: "memory"); else if (DK == 128) asm volatile("s_waitcnt vmcnt(4)" ::: "memory"); else asm volatile("s_waitcnt vmcnt(3)" ::: "memory"); } while (0)
; #define RESC(a) do { if (__any((a) < 1.f)) { if (hi == 0) al_l[r32] = (a); asm volatile("s_waitcnt lgkmcnt(0)" ::: "memory"); \
;     _Pragma("unroll") for (int d = 0; d < 4; ++d) _Pragma("unroll") for (int r = 0; r < 16; ++r) o[d][r] *= al_l[crow(r, hi)]; } } while (0)
; __device__ __forceinline__ void partialSM(f32x16& p0, f32x16& p1, float& m_reg, float& mn, float& alpha, float C, float thrRaw) {
;   float pmax = p0[0];
; #pragma unroll
;   for (int r = 1; r < 16; ++r) pmax = fmaxf(pmax, p0[r]);
; #pragma unroll
;   for (int r = 0; r < 16; ++r) pmax = fmaxf(pmax, p1[r]);
;   { auto rr = __builtin_amdgcn_permlane32_swap(__float_as_uint(pmax), __float_as_uint(pmax), false, false);
;     pmax = fmaxf(__uint_as_float(rr[0]), __uint_as_float(rr[1])); }
;   if (__builtin_expect(__all(pmax - m_reg <= thrRaw), 1)) { mn = m_reg; alpha = 1.f; }
;   else { mn = fmaxf(m_reg, pmax); alpha = __builtin_amdgcn_exp2f((m_reg - mn) * C); m_reg = mn; }
; template <int D0> __device__ __forceinline__ void pv_one(f32x16& od, int vb, bf16x8 pa0, bf16x8 pa1, bf16x8 pa2, bf16x8 pa3) {
;     ...
;   od = __builtin_amdgcn_mfma_f32_32x32x16_bf16(pa0, PK(l0, h0), od, 0, 0, 0);
;   od = __builtin_amdgcn_mfma_f32_32x32x16_bf16(pa1, PK(l1, h1), od, 0, 0, 0);
;   od = __builtin_amdgcn_mfma_f32_32x32x16_bf16(pa2, PK(l2, h2), od, 0, 0, 0);
;   od = __builtin_amdgcn_mfma_f32_32x32x16_bf16(pa3, PK(l3, h3), od, 0, 0, 0);
; template <int DK, bool NA, bool QL, int SD> ...
;     ...
;     __syncthreads(); SWAIT(); SWRITE(0, SE);
;     RESC(alB); __syncthreads();
	v_mfma_f32_32x32x16_bf16 v[50:65], v[138:141], v[226:229], v[50:65]
	ds_read_b64_tr_b16 v[226:227], v211 offset:0x600
	ds_read_b64_tr_b16 v[228:229], v211 offset:0xe00
	v_mfma_f32_32x32x16_bf16 v[50:65], v[222:225], v[230:233], v[50:65]
	ds_read_b64_tr_b16 v[230:231], v211 offset:0x1600
	ds_read_b64_tr_b16 v[232:233], v211 offset:0x1e00
	v_mfma_f32_32x32x16_bf16 v[50:65], v[144:147], v[234:237], v[50:65]
	ds_read_b64_tr_b16 v[234:235], v211 offset:0x2600
	ds_read_b64_tr_b16 v[236:237], v211 offset:0x2e00
	v_mfma_f32_32x32x16_bf16 v[50:65], v[148:151], v[238:241], v[50:65]
	ds_read_b64_tr_b16 v[238:239], v211 offset:0x3600
	ds_read_b64_tr_b16 v[240:241], v211 offset:0x3e00
	s_waitcnt lgkmcnt(0)
	v_mfma_f32_32x32x16_bf16 v[34:49], v[138:141], v[226:229], v[34:49]
	v_max_f32_e32 v138, v83, v83
	v_max_f32_e32 v139, v82, v82
	v_max_f32_e32 v138, v139, v138
	v_max3_f32 v138, v138, v84, v85
	v_max3_f32 v138, v138, v86, v87
	v_max3_f32 v138, v138, v88, v89
	v_max3_f32 v138, v138, v90, v91
	v_max3_f32 v138, v138, v92, v93
	v_max3_f32 v138, v138, v94, v95
	v_mfma_f32_32x32x16_bf16 v[34:49], v[222:225], v[230:233], v[34:49]
	v_max3_f32 v138, v138, v96, v97
	v_max3_f32 v138, v138, v66, v67
	v_max3_f32 v138, v138, v68, v69
	v_max3_f32 v138, v138, v70, v71
	v_max3_f32 v138, v138, v72, v73
	v_max3_f32 v138, v138, v74, v75
	v_max3_f32 v138, v138, v76, v77
	v_max3_f32 v138, v138, v78, v79
	v_mfma_f32_32x32x16_bf16 v[34:49], v[144:147], v[234:237], v[34:49]
	v_max3_f32 v138, v138, v80, v81
	v_mov_b32_e32 v139, v138
	s_nop 1
	v_permlane32_swap_b32_e32 v138, v139
	v_max_f32_e32 v139, v139, v139
	v_max_f32_e32 v138, v138, v138
	v_max_f32_e32 v138, v138, v139
	v_sub_f32_e32 v139, v138, v142
	s_mov_b32 s2, 0x42800000
	v_cmp_ge_f32_e32 vcc, s2, v139
	v_max_f32_e32 v139, v142, v142
	v_max_f32_e32 v138, v139, v138
	v_mfma_f32_32x32x16_bf16 v[34:49], v[148:151], v[238:241], v[34:49]
	v_sub_f32_e32 v139, v142, v138
	v_mul_f32_e32 v139, 0x3e38aa3b, v139
	v_exp_f32_e32 v139, v139
	s_cmp_eq_u64 vcc, exec
	s_cselect_b64 s[2:3], -1, 0
	s_barrier
	s_waitcnt vmcnt(3)
	v_cndmask_b32_e64 v222, v139, 1.0, s[2:3]
	v_cmp_gt_f32_e32 vcc, 1.0, v222
	s_waitcnt vmcnt(3)
	ds_write_b128 v214, v[114:117]
	ds_write_b128 v215, v[118:121]
	ds_write_b128 v213, v[122:125] offset:32768
	s_cbranch_vccz .LBB0_686
	s_and_saveexec_b64 s[4:5], s[0:1]
	ds_write_b32 v208, v222 offset:128
	s_or_b64 exec, exec, s[4:5]
	s_waitcnt lgkmcnt(0)
	v_add_u32_e32 v139, v207, v0
	ds_read_b128 v[144:147], v139 offset:128
	ds_read_b128 v[148:151], v139 offset:160
	ds_read_b128 v[224:227], v139 offset:192
	ds_read_b128 v[228:231], v139 offset:224
	s_waitcnt lgkmcnt(3)
	v_pk_mul_f32 v[2:3], v[144:145], v[2:3]
	v_pk_mul_f32 v[4:5], v[4:5], v[146:147]
	s_waitcnt lgkmcnt(2)
	v_pk_mul_f32 v[6:7], v[6:7], v[148:149]
	v_pk_mul_f32 v[8:9], v[8:9], v[150:151]
	s_waitcnt lgkmcnt(1)
	v_pk_mul_f32 v[10:11], v[10:11], v[224:225]
	v_pk_mul_f32 v[12:13], v[12:13], v[226:227]
	s_waitcnt lgkmcnt(0)
	v_pk_mul_f32 v[14:15], v[14:15], v[228:229]
	v_pk_mul_f32 v[30:31], v[30:31], v[228:229]
	v_pk_mul_f32 v[26:27], v[26:27], v[224:225]
	v_pk_mul_f32 v[22:23], v[22:23], v[148:149]
	v_pk_mul_f32 v[32:33], v[32:33], v[230:231]
	v_pk_mul_f32 v[28:29], v[28:29], v[226:227]
	v_pk_mul_f32 v[24:25], v[24:25], v[150:151]
	v_pk_mul_f32 v[20:21], v[20:21], v[146:147]
	v_pk_mul_f32 v[18:19], v[18:19], v[144:145]
	v_pk_mul_f32 v[16:17], v[16:17], v[230:231]
	v_pk_mul_f32 v[34:35], v[144:145], v[34:35]
	v_pk_mul_f32 v[36:37], v[36:37], v[146:147]
	v_pk_mul_f32 v[38:39], v[38:39], v[148:149]
	v_pk_mul_f32 v[40:41], v[40:41], v[150:151]
	v_pk_mul_f32 v[42:43], v[42:43], v[224:225]
	v_pk_mul_f32 v[44:45], v[44:45], v[226:227]
	v_pk_mul_f32 v[46:47], v[46:47], v[228:229]
	v_pk_mul_f32 v[62:63], v[62:63], v[228:229]
	v_pk_mul_f32 v[58:59], v[58:59], v[224:225]
	v_pk_mul_f32 v[54:55], v[54:55], v[148:149]
	v_pk_mul_f32 v[64:65], v[64:65], v[230:231]
	v_pk_mul_f32 v[60:61], v[60:61], v[226:227]
	v_pk_mul_f32 v[56:57], v[56:57], v[150:151]
	v_pk_mul_f32 v[52:53], v[52:53], v[146:147]
	v_pk_mul_f32 v[50:51], v[50:51], v[144:145]
	v_pk_mul_f32 v[48:49], v[48:49], v[230:231]
; #define SBAR() __builtin_amdgcn_sched_barrier(0)
; #define SLOAD(i, k0) do { sr_[i].vs0 = *reinterpret_cast<const bf16x8*>(&Vh[(long)((k0) + sr) * LDP + sc]); sr_[i].vs1 = *reinterpret_cast<const bf16x8*>(&Vh[(long)((k0) + 32 + sr) * LDP + sc]); \
;     sr_[i].ks0 = *reinterpret_cast<const bf16x8*>(&Kh[(long)((k0) + ksr) * LDP + ksc]); if (DK == 128) sr_[i].ks1 = *reinterpret_cast<const bf16x8*>(&Kh[(long)((k0) + 32 + ksr) * LDP + ksc]); } while (0)
; #define HOOK(P0, P1, j) do { if (NA) na_hook(P0, P1, krow0 + (j), q_row, q_col, win_r, win_c, rpb, inv_scale, hi); } while (0)
; __device__ __forceinline__ void partialSM(f32x16& p0, f32x16& p1, float& m_reg, float& mn, float& alpha, float C, float thrRaw) {
;     ...
;   float mnC = -mn * C;
; #pragma unroll
;   for (int r = 0; r < 16; ++r) p0[r] = fmaf(p0[r], C, mnC);
; #pragma unroll
;   for (int r = 0; r < 16; ++r) p1[r] = fmaf(p1[r], C, mnC);
; #pragma unroll
;   for (int r = 0; r < 16; ++r) p0[r] = __builtin_amdgcn_exp2f(p0[r]);
; template <int DK, bool QL>
; __device__ __forceinline__ void qkt(f32x16& p0, f32x16& p1, const bf16* Ks, const bf16x8* qr, const char* ql, int r32, int hi) {
;   p0 = f32x16{}; p1 = f32x16{};
; #pragma unroll
;   for (int d0 = 0; d0 < DK / 16; ++d0) { int cb = (d0 * 16 + hi * 8) * 2;
;     const bf16x8 qv = QL ? *reinterpret_cast<const bf16x8*>(ql + d0 * 1024) : qr[d0];
;     bf16x8 b0 = *reinterpret_cast<const bf16x8*>((const char*)Ks + kswz<DK>(r32, cb));
;     bf16x8 b1 = *reinterpret_cast<const bf16x8*>((const char*)Ks + kswz<DK>(32 + r32, cb));
;     p0 = __builtin_amdgcn_mfma_f32_32x32x16_bf16(b0, qv, p0, 0, 0, 0);
;     p1 = __builtin_amdgcn_mfma_f32_32x32x16_bf16(b1, qv, p1, 0, 0, 0); }
; template <int DK, bool NA, bool QL, int SD> ...
;     ...
;     SBAR(); qkt<DK, QL>(pA0, pA1, K_lds, qr, ql, r32, hi); HOOK(pA0, pA1, j + 1);
;     finishSM(pB0, pB1, alB, l_reg, pa0, pa1, pa2, pa3); SBAR();
;     if (SD == 1 || j + 3 < NT) SLOAD(SE, (j + 1 + SD) * KVBLK); SBAR();
.LBB0_686:
	v_cndmask_b32_e64 v223, v138, v142, s[2:3]
	v_mul_f32_e32 v224, 0xbe38aa3b, v223
	v_fmamk_f32 v82, v82, 0x3e38aa3b, v224
	v_fmamk_f32 v83, v83, 0x3e38aa3b, v224
	v_fmamk_f32 v84, v84, 0x3e38aa3b, v224
	v_fmamk_f32 v85, v85, 0x3e38aa3b, v224
	v_fmamk_f32 v86, v86, 0x3e38aa3b, v224
	v_fmamk_f32 v87, v87, 0x3e38aa3b, v224
	v_fmamk_f32 v88, v88, 0x3e38aa3b, v224
	v_fmamk_f32 v89, v89, 0x3e38aa3b, v224
	v_fmamk_f32 v90, v90, 0x3e38aa3b, v224
	v_fmamk_f32 v91, v91, 0x3e38aa3b, v224
	v_fmamk_f32 v92, v92, 0x3e38aa3b, v224
	v_fmamk_f32 v93, v93, 0x3e38aa3b, v224
	v_fmamk_f32 v94, v94, 0x3e38aa3b, v224
	v_fmamk_f32 v95, v95, 0x3e38aa3b, v224
	v_fmamk_f32 v96, v96, 0x3e38aa3b, v224
	v_fmamk_f32 v97, v97, 0x3e38aa3b, v224
	v_exp_f32_e32 v138, v82
	v_exp_f32_e32 v153, v83
	v_exp_f32_e32 v139, v84
	v_exp_f32_e32 v152, v85
	v_exp_f32_e32 v140, v86
	v_exp_f32_e32 v151, v87
	v_exp_f32_e32 v141, v88
	v_exp_f32_e32 v150, v89
	v_exp_f32_e32 v142, v90
	v_exp_f32_e32 v149, v91
	v_exp_f32_e32 v143, v92
	v_exp_f32_e32 v148, v93
	v_exp_f32_e32 v144, v94
	v_exp_f32_e32 v147, v95
	v_exp_f32_e32 v145, v96
	v_exp_f32_e32 v146, v97
	v_fmamk_f32 v233, v66, 0x3e38aa3b, v224
	v_fmamk_f32 v234, v67, 0x3e38aa3b, v224
	v_fmamk_f32 v235, v68, 0x3e38aa3b, v224
	v_fmamk_f32 v236, v69, 0x3e38aa3b, v224
	v_fmamk_f32 v237, v70, 0x3e38aa3b, v224
	v_fmamk_f32 v226, v71, 0x3e38aa3b, v224
	v_fmamk_f32 v227, v72, 0x3e38aa3b, v224
	v_fmamk_f32 v228, v73, 0x3e38aa3b, v224
	v_fmamk_f32 v229, v74, 0x3e38aa3b, v224
	v_fmamk_f32 v230, v75, 0x3e38aa3b, v224
	v_fmamk_f32 v231, v76, 0x3e38aa3b, v224
	v_fmamk_f32 v232, v77, 0x3e38aa3b, v224
	v_fmamk_f32 v225, v78, 0x3e38aa3b, v224
	v_fmamk_f32 v238, v79, 0x3e38aa3b, v224
	v_fmamk_f32 v239, v80, 0x3e38aa3b, v224
	v_fmac_f32_e32 v224, 0x3e38aa3b, v81
	s_waitcnt lgkmcnt(0)
	s_barrier
	ds_read_b128 v[66:69], v212 offset:32768
	ds_read_b128 v[70:73], v212 offset:36864
	ds_read_b128 v[182:185], v217 offset:32768
	ds_read_b128 v[190:193], v217 offset:36864
	ds_read_b128 v[168:171], v218 offset:32768
	ds_read_b128 v[194:197], v218 offset:36864
	v_exp_f32_e32 v164, v233
	v_exp_f32_e32 v233, v224
	v_add_f32_e32 v224, 0, v138
	v_add_f32_e32 v224, v153, v224
	s_waitcnt lgkmcnt(5)
	v_mfma_f32_32x32x16_bf16 v[82:97], v[66:69], v[110:113], 0
	v_add_f32_e32 v224, v139, v224
	v_add_f32_e32 v224, v152, v224
	v_add_f32_e32 v224, v140, v224
	ds_read_b128 v[240:243], v216 offset:32768
	ds_read_b128 v[244:247], v216 offset:36864
	v_add_f32_e32 v224, v151, v224
	v_add_f32_e32 v224, v141, v224
	v_add_f32_e32 v224, v150, v224
	s_waitcnt lgkmcnt(6)
	v_mfma_f32_32x32x16_bf16 v[66:81], v[70:73], v[110:113], 0
	v_add_f32_e32 v224, v142, v224
	v_add_f32_e32 v224, v149, v224
	v_add_f32_e32 v224, v143, v224
	v_add_f32_e32 v224, v148, v224
	v_add_f32_e32 v224, v144, v224
	v_exp_f32_e32 v165, v234
	v_add_f32_e32 v224, v147, v224
	s_waitcnt lgkmcnt(1)
	v_mfma_f32_32x32x16_bf16 v[82:97], v[240:243], v[106:109], v[82:97]
	v_exp_f32_e32 v166, v235
	v_add_f32_e32 v224, v145, v224
	v_exp_f32_e32 v167, v236
	v_add_f32_e32 v224, v146, v224
	v_exp_f32_e32 v172, v237
	v_add_f32_e32 v224, v164, v224
	v_exp_f32_e32 v173, v226
	s_waitcnt lgkmcnt(0)
	v_mfma_f32_32x32x16_bf16 v[66:81], v[244:247], v[106:109], v[66:81]
	v_add_f32_e32 v224, v165, v224
	v_exp_f32_e32 v174, v227
	v_add_f32_e32 v224, v166, v224
	v_exp_f32_e32 v175, v228
	v_add_f32_e32 v224, v167, v224
	v_exp_f32_e32 v226, v229
	s_waitcnt lgkmcnt(0)
	v_mfma_f32_32x32x16_bf16 v[82:97], v[182:185], v[98:101], v[82:97]
	v_add_f32_e32 v224, v172, v224
	v_exp_f32_e32 v227, v230
	v_add_f32_e32 v224, v173, v224
	v_exp_f32_e32 v228, v231
	v_add_f32_e32 v224, v174, v224
	v_exp_f32_e32 v229, v232
	v_add_f32_e32 v224, v175, v224
	s_waitcnt lgkmcnt(0)
	v_mfma_f32_32x32x16_bf16 v[66:81], v[190:193], v[98:101], v[66:81]
	v_exp_f32_e32 v230, v225
	v_add_f32_e32 v224, v226, v224
	v_exp_f32_e32 v231, v238
	v_add_f32_e32 v224, v227, v224
	v_exp_f32_e32 v232, v239
	v_add_f32_e32 v224, v228, v224
	s_waitcnt lgkmcnt(0)
	v_mfma_f32_32x32x16_bf16 v[82:97], v[168:171], v[102:105], v[82:97]
	v_add_f32_e32 v224, v229, v224
	v_add_f32_e32 v224, v230, v224
	v_add_f32_e32 v224, v231, v224
	v_add_f32_e32 v224, v232, v224
	v_add_f32_e32 v224, v233, v224
	v_mov_b32_e32 v225, v224
	v_cvt_pk_bf16_f32 v138, v138, v153
	s_waitcnt lgkmcnt(0)
	v_mfma_f32_32x32x16_bf16 v[66:81], v[194:197], v[102:105], v[66:81]
	v_cvt_pk_bf16_f32 v139, v139, v152
	v_cvt_pk_bf16_f32 v140, v140, v151
	v_cvt_pk_bf16_f32 v141, v141, v150
	v_cvt_pk_bf16_f32 v142, v142, v149
	v_cvt_pk_bf16_f32 v143, v143, v148
	v_cvt_pk_bf16_f32 v144, v144, v147
	v_cvt_pk_bf16_f32 v145, v145, v146
	v_cvt_pk_bf16_f32 v146, v164, v165
	v_cvt_pk_bf16_f32 v147, v166, v167
	v_cvt_pk_bf16_f32 v148, v172, v173
	v_cvt_pk_bf16_f32 v149, v174, v175
	v_cvt_pk_bf16_f32 v150, v226, v227
	v_cvt_pk_bf16_f32 v151, v228, v229
	v_cvt_pk_bf16_f32 v152, v230, v231
	v_cvt_pk_bf16_f32 v153, v232, v233
	v_permlane32_swap_b32_e32 v224, v225
	v_permlane32_swap_b32_e32 v138, v140
	v_permlane32_swap_b32_e32 v139, v141
	v_permlane32_swap_b32_e32 v142, v144
	v_permlane32_swap_b32_e32 v143, v145
	v_permlane32_swap_b32_e32 v146, v148
	v_permlane32_swap_b32_e32 v147, v149
	v_permlane32_swap_b32_e32 v150, v152
	v_permlane32_swap_b32_e32 v151, v153
	s_cmp_gt_u32 s9, 60
	s_cselect_b64 s[4:5], -1, 0
	s_and_b64 vcc, exec, s[4:5]
	s_cbranch_vccnz .LBB0_688
	v_add_co_u32_e32 v114, vcc, 0xe180000, v160
	s_nop 1
	v_addc_co_u32_e32 v115, vcc, 0, v161, vcc
	v_add_co_u32_e32 v118, vcc, 0xe1d0000, v160
	s_nop 1
	v_addc_co_u32_e32 v119, vcc, 0, v161, vcc
	v_add_co_u32_e32 v122, vcc, 0xe180000, v176
	global_load_dwordx4 v[114:117], v[114:115], off offset:2048
	s_nop 0
	global_load_dwordx4 v[118:121], v[118:119], off offset:2048
	v_addc_co_u32_e32 v123, vcc, 0, v177, vcc
	global_load_dwordx4 v[122:125], v[122:123], off offset:1024

; #define SBAR() __builtin_amdgcn_sched_barrier(0)
; #define SLOAD(i, k0) do { sr_[i].vs0 = *reinterpret_cast<const bf16x8*>(&Vh[(long)((k0) + sr) * LDP + sc]); sr_[i].vs1 = *reinterpret_cast<const bf16x8*>(&Vh[(long)((k0) + 32 + sr) * LDP + sc]); \
;     sr_[i].ks0 = *reinterpret_cast<const bf16x8*>(&Kh[(long)((k0) + ksr) * LDP + ksc]); if (DK == 128) sr_[i].ks1 = *reinterpret_cast<const bf16x8*>(&Kh[(long)((k0) + 32 + ksr) * LDP + ksc]); } while (0)
; #define HOOK(P0, P1, j) do { if (NA) na_hook(P0, P1, krow0 + (j), q_row, q_col, win_r, win_c, rpb, inv_scale, hi); } while (0)
; template <int DK, bool QL>
; __device__ __forceinline__ void qkt(f32x16& p0, f32x16& p1, const bf16* Ks, const bf16x8* qr, const char* ql, int r32, int hi) {
;   p0 = f32x16{}; p1 = f32x16{};
; #pragma unroll
;   for (int d0 = 0; d0 < DK / 16; ++d0) { int cb = (d0 * 16 + hi * 8) * 2;
;     const bf16x8 qv = QL ? *reinterpret_cast<const bf16x8*>(ql + d0 * 1024) : qr[d0];
;     bf16x8 b0 = *reinterpret_cast<const bf16x8*>((const char*)Ks + kswz<DK>(r32, cb));
;     bf16x8 b1 = *reinterpret_cast<const bf16x8*>((const char*)Ks + kswz<DK>(32 + r32, cb));
;     p0 = __builtin_amdgcn_mfma_f32_32x32x16_bf16(b0, qv, p0, 0, 0, 0);
;     p1 = __builtin_amdgcn_mfma_f32_32x32x16_bf16(b1, qv, p1, 0, 0, 0); }
; template <int DK, bool NA, bool QL, int SD> ...
;     ...
;     SBAR(); qkt<DK, QL>(pB0, pB1, (bf16*)((char*)K_lds + SHM_K), qr, ql, r32, hi); HOOK(pB0, pB1, j);
;     finishSM(pA0, pA1, alA, l_reg, pa0, pa1, pa2, pa3); SBAR();
;     SLOAD(SO, (j + SD) * KVBLK); SBAR();
;     pv_d0(o, vb0, pa0, pa1, pa2, pa3); partialSM(pB0, pB1, m_reg, mnB, alB, C, thrRaw);
.LBB0_701:
	ds_read_b128 v[66:69], v215 offset:49152
	ds_read_b128 v[70:73], v215 offset:53248
	ds_read_b128 v[182:185], v217 offset:49152
	ds_read_b128 v[190:193], v217 offset:53248
	ds_read_b128 v[168:171], v218 offset:49152
	ds_read_b128 v[194:197], v218 offset:53248
	v_exp_f32_e32 v143, v138
	v_add_f32_e32 v138, 0, v177
	v_add_f32_e32 v138, v226, v138
	s_waitcnt lgkmcnt(5)
	v_mfma_f32_32x32x16_bf16 v[82:97], v[66:69], v[110:113], 0
	v_add_f32_e32 v138, v161, v138
	v_add_f32_e32 v138, v223, v138
	v_add_f32_e32 v138, v153, v138
	ds_read_b128 v[228:231], v216 offset:49152
	ds_read_b128 v[232:235], v216 offset:53248
	v_add_f32_e32 v138, v176, v138
	v_add_f32_e32 v138, v152, v138
	v_add_f32_e32 v138, v160, v138
	s_waitcnt lgkmcnt(6)
	v_mfma_f32_32x32x16_bf16 v[66:81], v[70:73], v[110:113], 0
	v_add_f32_e32 v138, v149, v138
	v_add_f32_e32 v138, v151, v138
	v_add_f32_e32 v138, v147, v138
	v_add_f32_e32 v138, v150, v138
	v_add_f32_e32 v138, v145, v138
	v_exp_f32_e32 v164, v139
	v_add_f32_e32 v138, v148, v138
	s_waitcnt lgkmcnt(1)
	v_mfma_f32_32x32x16_bf16 v[82:97], v[228:231], v[106:109], v[82:97]
	v_exp_f32_e32 v136, v136
	v_add_f32_e32 v138, v144, v138
	v_exp_f32_e32 v137, v137
	v_add_f32_e32 v138, v146, v138
	v_exp_f32_e32 v130, v130
	v_add_f32_e32 v138, v143, v138
	v_exp_f32_e32 v131, v131
	s_waitcnt lgkmcnt(0)
	v_mfma_f32_32x32x16_bf16 v[66:81], v[232:235], v[106:109], v[66:81]
	v_add_f32_e32 v138, v164, v138
	v_exp_f32_e32 v128, v128
	v_add_f32_e32 v138, v136, v138
	v_exp_f32_e32 v129, v129
	v_add_f32_e32 v138, v137, v138
	v_exp_f32_e32 v126, v126
	s_waitcnt lgkmcnt(0)
	v_mfma_f32_32x32x16_bf16 v[82:97], v[182:185], v[102:105], v[82:97]
	v_add_f32_e32 v138, v130, v138
	v_exp_f32_e32 v127, v127
	v_add_f32_e32 v138, v131, v138
	v_exp_f32_e32 v165, v140
	v_add_f32_e32 v138, v128, v138
	v_exp_f32_e32 v166, v141
	v_add_f32_e32 v138, v129, v138
	s_waitcnt lgkmcnt(0)
	v_mfma_f32_32x32x16_bf16 v[66:81], v[190:193], v[102:105], v[66:81]
	v_exp_f32_e32 v134, v134
	v_add_f32_e32 v138, v126, v138
	v_exp_f32_e32 v135, v135
	v_add_f32_e32 v138, v127, v138
	v_exp_f32_e32 v132, v132
	v_add_f32_e32 v138, v165, v138
	s_waitcnt lgkmcnt(0)
	v_mfma_f32_32x32x16_bf16 v[82:97], v[168:171], v[98:101], v[82:97]
	v_exp_f32_e32 v133, v133
	v_add_f32_e32 v138, v166, v138
	v_add_f32_e32 v138, v134, v138
	v_add_f32_e32 v138, v135, v138
	v_add_f32_e32 v138, v132, v138
	v_add_f32_e32 v220, v133, v138
	v_mov_b32_e32 v221, v220
	s_waitcnt lgkmcnt(0)
	v_mfma_f32_32x32x16_bf16 v[66:81], v[194:197], v[98:101], v[66:81]
	v_cvt_pk_bf16_f32 v138, v177, v226
	v_cvt_pk_bf16_f32 v139, v161, v223
	v_cvt_pk_bf16_f32 v140, v153, v176
	v_cvt_pk_bf16_f32 v141, v152, v160
	v_cvt_pk_bf16_f32 v222, v149, v151
	v_cvt_pk_bf16_f32 v223, v147, v150
	v_cvt_pk_bf16_f32 v224, v145, v148
	v_permlane32_swap_b32_e32 v220, v221
	v_permlane32_swap_b32_e32 v138, v140
	v_cvt_pk_bf16_f32 v225, v144, v146
	v_permlane32_swap_b32_e32 v222, v224
	v_cvt_pk_bf16_f32 v144, v143, v164
	v_cvt_pk_bf16_f32 v145, v136, v137
	v_cvt_pk_bf16_f32 v146, v130, v131
	v_cvt_pk_bf16_f32 v147, v128, v129
	v_cvt_pk_bf16_f32 v148, v126, v127
	v_cvt_pk_bf16_f32 v149, v165, v166
	v_cvt_pk_bf16_f32 v150, v134, v135
	v_cvt_pk_bf16_f32 v151, v132, v133
	v_permlane32_swap_b32_e32 v139, v141
	v_permlane32_swap_b32_e32 v223, v225
	v_permlane32_swap_b32_e32 v144, v146
	v_permlane32_swap_b32_e32 v145, v147
	v_permlane32_swap_b32_e32 v148, v150
	v_permlane32_swap_b32_e32 v149, v151
	v_readlane_b32 s2, v254, 32
	v_readlane_b32 s3, v254, 33
	s_mov_b32 s4, 0xe0e0000
	s_mov_b32 s5, 0xe130000
	v_lshl_add_u64 v[160:161], v[156:157], 0, s[2:3]
	v_add_co_u32_e32 v126, vcc, s4, v160
	v_lshl_add_u64 v[176:177], v[158:159], 0, s[2:3]
	s_nop 0
	v_addc_co_u32_e32 v127, vcc, 0, v161, vcc
	v_add_co_u32_e32 v130, vcc, s5, v160
	s_nop 1
	v_addc_co_u32_e32 v131, vcc, 0, v161, vcc
	v_add_co_u32_e32 v134, vcc, s4, v176
	global_load_dwordx4 v[126:129], v[126:127], off offset:2048
	s_nop 0
	global_load_dwordx4 v[130:133], v[130:131], off offset:2048
	v_addc_co_u32_e32 v135, vcc, 0, v177, vcc
	global_load_dwordx4 v[134:137], v[134:135], off offset:1152
	ds_read_b64_tr_b16 v[226:227], v211 offset:0
	ds_read_b64_tr_b16 v[228:229], v211 offset:0x800
	ds_read_b64_tr_b16 v[230:231], v211 offset:0x1000
	ds_read_b64_tr_b16 v[232:233], v211 offset:0x1800
	ds_read_b64_tr_b16 v[234:235], v211 offset:0x2000
	ds_read_b64_tr_b16 v[236:237], v211 offset:0x2800
	ds_read_b64_tr_b16 v[238:239], v211 offset:0x3000
	ds_read_b64_tr_b16 v[240:241], v211 offset:0x3800
	s_waitcnt lgkmcnt(0)
	s_nop 0
	v_mfma_f32_32x32x16_bf16 v[2:17], v[138:141], v[226:229], v[2:17]
	ds_read_b64_tr_b16 v[226:227], v211 offset:0x200
	ds_read_b64_tr_b16 v[228:229], v211 offset:0xa00
	v_mfma_f32_32x32x16_bf16 v[2:17], v[222:225], v[230:233], v[2:17]
	ds_read_b64_tr_b16 v[230:231], v211 offset:0x1200
	ds_read_b64_tr_b16 v[232:233], v211 offset:0x1a00
	v_mfma_f32_32x32x16_bf16 v[2:17], v[144:147], v[234:237], v[2:17]
	ds_read_b64_tr_b16 v[234:235], v211 offset:0x2200
	ds_read_b64_tr_b16 v[236:237], v211 offset:0x2a00
	v_mfma_f32_32x32x16_bf16 v[2:17], v[148:151], v[238:241], v[2:17]
	ds_read_b64_tr_b16 v[238:239], v211 offset:0x3200
	ds_read_b64_tr_b16 v[240:241], v211 offset:0x3a00
	s_waitcnt lgkmcnt(0)
	v_mfma_f32_32x32x16_bf16 v[50:65], v[138:141], v[226:229], v[50:65]
	ds_read_b64_tr_b16 v[226:227], v211 offset:0x400
	ds_read_b64_tr_b16 v[228:229], v211 offset:0xc00
	v_mfma_f32_32x32x16_bf16 v[50:65], v[222:225], v[230:233], v[50:65]
	ds_read_b64_tr_b16 v[230:231], v211 offset:0x1400
	ds_read_b64_tr_b16 v[232:233], v211 offset:0x1c00
	v_mfma_f32_32x32x16_bf16 v[50:65], v[144:147], v[234:237], v[50:65]
	ds_read_b64_tr_b16 v[234:235], v211 offset:0x2400
	ds_read_b64_tr_b16 v[236:237], v211 offset:0x2c00
	v_mfma_f32_32x32x16_bf16 v[50:65], v[148:151], v[238:241], v[50:65]
	ds_read_b64_tr_b16 v[238:239], v211 offset:0x3400
	ds_read_b64_tr_b16 v[240:241], v211 offset:0x3c00
	s_waitcnt lgkmcnt(0)
; #define SWAIT() do { if (SD == 1) asm volatile("s_waitcnt vmcnt(0)" ::: "memory"); else if (DK == 128) asm volatile("s_waitcnt vmcnt(4)" ::: "memory"); else asm volatile("s_waitcnt vmcnt(3)" ::: "memory"); } while (0)
; #define RESC(a) do { if (__any((a) < 1.f)) { if (hi == 0) al_l[r32] = (a); asm volatile("s_waitcnt lgkmcnt(0)" ::: "memory"); \
;     _Pragma("unroll") for (int d = 0; d < 4; ++d) _Pragma("unroll") for (int r = 0; r < 16; ++r) o[d][r] *= al_l[crow(r, hi)]; } } while (0)
; __device__ __forceinline__ void partialSM(f32x16& p0, f32x16& p1, float& m_reg, float& mn, float& alpha, float C, float thrRaw) {
;   float pmax = p0[0];
; #pragma unroll
;   for (int r = 1; r < 16; ++r) pmax = fmaxf(pmax, p0[r]);
; #pragma unroll
;   for (int r = 0; r < 16; ++r) pmax = fmaxf(pmax, p1[r]);
;   { auto rr = __builtin_amdgcn_permlane32_swap(__float_as_uint(pmax), __float_as_uint(pmax), false, false);
;     pmax = fmaxf(__uint_as_float(rr[0]), __uint_as_float(rr[1])); }
;   if (__builtin_expect(__all(pmax - m_reg <= thrRaw), 1)) { mn = m_reg; alpha = 1.f; }
;   else { mn = fmaxf(m_reg, pmax); alpha = __builtin_amdgcn_exp2f((m_reg - mn) * C); m_reg = mn; }
; template <int D0> __device__ __forceinline__ void pv_one(f32x16& od, int vb, bf16x8 pa0, bf16x8 pa1, bf16x8 pa2, bf16x8 pa3) {
;     ...
;   od = __builtin_amdgcn_mfma_f32_32x32x16_bf16(pa0, PK(l0, h0), od, 0, 0, 0);
;   od = __builtin_amdgcn_mfma_f32_32x32x16_bf16(pa1, PK(l1, h1), od, 0, 0, 0);
;   od = __builtin_amdgcn_mfma_f32_32x32x16_bf16(pa2, PK(l2, h2), od, 0, 0, 0);
;   od = __builtin_amdgcn_mfma_f32_32x32x16_bf16(pa3, PK(l3, h3), od, 0, 0, 0);
; template <int DK, bool NA, bool QL, int SD> ...
;     ...
;     __syncthreads(); SWAIT(); SWRITE(0, SE);
;     RESC(alB); __syncthreads();
	v_mfma_f32_32x32x16_bf16 v[34:49], v[138:141], v[226:229], v[34:49]
	ds_read_b64_tr_b16 v[226:227], v211 offset:0x600
	ds_read_b64_tr_b16 v[228:229], v211 offset:0xe00
	v_mfma_f32_32x32x16_bf16 v[34:49], v[222:225], v[230:233], v[34:49]
	ds_read_b64_tr_b16 v[230:231], v211 offset:0x1600
	ds_read_b64_tr_b16 v[232:233], v211 offset:0x1e00
	v_mfma_f32_32x32x16_bf16 v[34:49], v[144:147], v[234:237], v[34:49]
	ds_read_b64_tr_b16 v[234:235], v211 offset:0x2600
	ds_read_b64_tr_b16 v[236:237], v211 offset:0x2e00
	v_mfma_f32_32x32x16_bf16 v[34:49], v[148:151], v[238:241], v[34:49]
	ds_read_b64_tr_b16 v[238:239], v211 offset:0x3600
	ds_read_b64_tr_b16 v[240:241], v211 offset:0x3e00
	s_waitcnt lgkmcnt(0)
	v_mfma_f32_32x32x16_bf16 v[18:33], v[138:141], v[226:229], v[18:33]
	v_max_f32_e32 v138, v83, v83
	v_max_f32_e32 v139, v82, v82
	v_max_f32_e32 v138, v139, v138
	v_max3_f32 v138, v138, v84, v85
	v_max3_f32 v138, v138, v86, v87
	v_max3_f32 v138, v138, v88, v89
	v_max3_f32 v138, v138, v90, v91
	v_max3_f32 v138, v138, v92, v93
	v_max3_f32 v138, v138, v94, v95
	v_mfma_f32_32x32x16_bf16 v[18:33], v[222:225], v[230:233], v[18:33]
	v_max3_f32 v138, v138, v96, v97
	v_max3_f32 v138, v138, v66, v67
	v_max3_f32 v138, v138, v68, v69
	v_max3_f32 v138, v138, v70, v71
	v_max3_f32 v138, v138, v72, v73
	v_max3_f32 v138, v138, v74, v75
	v_max3_f32 v138, v138, v76, v77
	v_max3_f32 v138, v138, v78, v79
	v_mfma_f32_32x32x16_bf16 v[18:33], v[144:147], v[234:237], v[18:33]
	v_max3_f32 v138, v138, v80, v81
	v_mov_b32_e32 v139, v138
	s_nop 1
	v_permlane32_swap_b32_e32 v138, v139
	v_max_f32_e32 v139, v139, v139
	v_max_f32_e32 v138, v138, v138
	v_max_f32_e32 v138, v138, v139
	v_sub_f32_e32 v139, v138, v142
	s_mov_b32 s2, 0x42800000
	v_cmp_ge_f32_e32 vcc, s2, v139
	v_max_f32_e32 v139, v142, v142
	v_max_f32_e32 v138, v139, v138
	v_mfma_f32_32x32x16_bf16 v[18:33], v[148:151], v[238:241], v[18:33]
	v_sub_f32_e32 v139, v142, v138
	v_mul_f32_e32 v139, 0x3e38aa3b, v139
	v_exp_f32_e32 v139, v139
	s_cmp_eq_u64 vcc, exec
	s_cselect_b64 s[2:3], -1, 0
	s_barrier
	s_waitcnt vmcnt(3)
	v_cndmask_b32_e64 v222, v139, 1.0, s[2:3]
	v_cmp_gt_f32_e32 vcc, 1.0, v222
	s_waitcnt vmcnt(3)
	ds_write_b128 v212, v[114:117]
	ds_write_b128 v213, v[118:121]
	ds_write_b128 v214, v[122:125] offset:32768
	s_cbranch_vccz .LBB0_705
	s_and_saveexec_b64 s[4:5], s[0:1]
	ds_write_b32 v208, v222 offset:128
	s_or_b64 exec, exec, s[4:5]
	s_waitcnt lgkmcnt(0)
	v_add_u32_e32 v139, v207, v0
	ds_read_b128 v[144:147], v139 offset:224
	ds_read_b128 v[148:151], v139 offset:192
	ds_read_b128 v[224:227], v139 offset:160
	ds_read_b128 v[228:231], v139 offset:128
	s_waitcnt lgkmcnt(3)
	v_pk_mul_f32 v[14:15], v[14:15], v[144:145]
	s_waitcnt lgkmcnt(2)
	v_pk_mul_f32 v[10:11], v[10:11], v[148:149]
	s_waitcnt lgkmcnt(1)
	v_pk_mul_f32 v[6:7], v[6:7], v[224:225]
	v_pk_mul_f32 v[16:17], v[16:17], v[146:147]
	v_pk_mul_f32 v[12:13], v[12:13], v[150:151]
	v_pk_mul_f32 v[8:9], v[8:9], v[226:227]
	s_waitcnt lgkmcnt(0)
	v_pk_mul_f32 v[4:5], v[4:5], v[230:231]
	v_pk_mul_f32 v[2:3], v[2:3], v[228:229]
	v_pk_mul_f32 v[62:63], v[144:145], v[62:63]
	v_pk_mul_f32 v[58:59], v[148:149], v[58:59]
	v_pk_mul_f32 v[54:55], v[224:225], v[54:55]
	v_pk_mul_f32 v[64:65], v[146:147], v[64:65]
	v_pk_mul_f32 v[60:61], v[150:151], v[60:61]
	v_pk_mul_f32 v[56:57], v[226:227], v[56:57]
	v_pk_mul_f32 v[52:53], v[230:231], v[52:53]
	v_pk_mul_f32 v[50:51], v[228:229], v[50:51]
	v_pk_mul_f32 v[46:47], v[144:145], v[46:47]
	v_pk_mul_f32 v[42:43], v[148:149], v[42:43]
	v_pk_mul_f32 v[38:39], v[224:225], v[38:39]
	v_pk_mul_f32 v[48:49], v[146:147], v[48:49]
	v_pk_mul_f32 v[44:45], v[150:151], v[44:45]
	v_pk_mul_f32 v[40:41], v[226:227], v[40:41]
	v_pk_mul_f32 v[36:37], v[230:231], v[36:37]
	v_pk_mul_f32 v[34:35], v[228:229], v[34:35]
	v_pk_mul_f32 v[30:31], v[144:145], v[30:31]
	v_pk_mul_f32 v[26:27], v[148:149], v[26:27]
	v_pk_mul_f32 v[22:23], v[224:225], v[22:23]
	v_pk_mul_f32 v[32:33], v[146:147], v[32:33]
	v_pk_mul_f32 v[28:29], v[150:151], v[28:29]
	v_pk_mul_f32 v[24:25], v[226:227], v[24:25]
	v_pk_mul_f32 v[20:21], v[230:231], v[20:21]
	v_pk_mul_f32 v[18:19], v[228:229], v[18:19]
; #define SBAR() __builtin_amdgcn_sched_barrier(0)
; #define SLOAD(i, k0) do { sr_[i].vs0 = *reinterpret_cast<const bf16x8*>(&Vh[(long)((k0) + sr) * LDP + sc]); sr_[i].vs1 = *reinterpret_cast<const bf16x8*>(&Vh[(long)((k0) + 32 + sr) * LDP + sc]); \
;     sr_[i].ks0 = *reinterpret_cast<const bf16x8*>(&Kh[(long)((k0) + ksr) * LDP + ksc]); if (DK == 128) sr_[i].ks1 = *reinterpret_cast<const bf16x8*>(&Kh[(long)((k0) + 32 + ksr) * LDP + ksc]); } while (0)
; #define HOOK(P0, P1, j) do { if (NA) na_hook(P0, P1, krow0 + (j), q_row, q_col, win_r, win_c, rpb, inv_scale, hi); } while (0)
; __device__ __forceinline__ void partialSM(f32x16& p0, f32x16& p1, float& m_reg, float& mn, float& alpha, float C, float thrRaw) {
;     ...
;   float mnC = -mn * C;
; #pragma unroll
;   for (int r = 0; r < 16; ++r) p0[r] = fmaf(p0[r], C, mnC);
; #pragma unroll
;   for (int r = 0; r < 16; ++r) p1[r] = fmaf(p1[r], C, mnC);
; #pragma unroll
;   for (int r = 0; r < 16; ++r) p0[r] = __builtin_amdgcn_exp2f(p0[r]);
; template <int DK, bool QL>
; __device__ __forceinline__ void qkt(f32x16& p0, f32x16& p1, const bf16* Ks, const bf16x8* qr, const char* ql, int r32, int hi) {
;   p0 = f32x16{}; p1 = f32x16{};
; #pragma unroll
;   for (int d0 = 0; d0 < DK / 16; ++d0) { int cb = (d0 * 16 + hi * 8) * 2;
;     const bf16x8 qv = QL ? *reinterpret_cast<const bf16x8*>(ql + d0 * 1024) : qr[d0];
;     bf16x8 b0 = *reinterpret_cast<const bf16x8*>((const char*)Ks + kswz<DK>(r32, cb));
;     bf16x8 b1 = *reinterpret_cast<const bf16x8*>((const char*)Ks + kswz<DK>(32 + r32, cb));
;     p0 = __builtin_amdgcn_mfma_f32_32x32x16_bf16(b0, qv, p0, 0, 0, 0);
;     p1 = __builtin_amdgcn_mfma_f32_32x32x16_bf16(b1, qv, p1, 0, 0, 0); }
; template <int DK, bool NA, bool QL, int SD> ...
;     ...
;     SBAR(); qkt<DK, QL>(pA0, pA1, K_lds, qr, ql, r32, hi); HOOK(pA0, pA1, j + 1);
;     finishSM(pB0, pB1, alB, l_reg, pa0, pa1, pa2, pa3); SBAR();
;     if (SD == 1 || j + 3 < NT) SLOAD(SE, (j + 1 + SD) * KVBLK); SBAR();
.LBB0_705:
	v_cndmask_b32_e64 v223, v138, v142, s[2:3]
	v_mul_f32_e32 v224, 0xbe38aa3b, v223
	v_fmamk_f32 v82, v82, 0x3e38aa3b, v224
	v_fmamk_f32 v83, v83, 0x3e38aa3b, v224
	v_fmamk_f32 v84, v84, 0x3e38aa3b, v224
	v_fmamk_f32 v85, v85, 0x3e38aa3b, v224
	v_fmamk_f32 v86, v86, 0x3e38aa3b, v224
	v_fmamk_f32 v87, v87, 0x3e38aa3b, v224
	v_fmamk_f32 v88, v88, 0x3e38aa3b, v224
	v_fmamk_f32 v89, v89, 0x3e38aa3b, v224
	v_fmamk_f32 v90, v90, 0x3e38aa3b, v224
	v_fmamk_f32 v91, v91, 0x3e38aa3b, v224
	v_fmamk_f32 v92, v92, 0x3e38aa3b, v224
	v_fmamk_f32 v93, v93, 0x3e38aa3b, v224
	v_fmamk_f32 v94, v94, 0x3e38aa3b, v224
	v_fmamk_f32 v95, v95, 0x3e38aa3b, v224
	v_fmamk_f32 v96, v96, 0x3e38aa3b, v224
	v_fmamk_f32 v97, v97, 0x3e38aa3b, v224
	v_exp_f32_e32 v138, v82
	v_exp_f32_e32 v153, v83
	v_exp_f32_e32 v139, v84
	v_exp_f32_e32 v152, v85
	v_exp_f32_e32 v140, v86
	v_exp_f32_e32 v151, v87
	v_exp_f32_e32 v141, v88
	v_exp_f32_e32 v150, v89
	v_exp_f32_e32 v142, v90
	v_exp_f32_e32 v149, v91
	v_exp_f32_e32 v143, v92
	v_exp_f32_e32 v148, v93
	v_exp_f32_e32 v144, v94
	v_exp_f32_e32 v147, v95
	v_exp_f32_e32 v145, v96
	v_exp_f32_e32 v146, v97
	v_fmamk_f32 v233, v66, 0x3e38aa3b, v224
	v_fmamk_f32 v234, v67, 0x3e38aa3b, v224
	v_fmamk_f32 v235, v68, 0x3e38aa3b, v224
	v_fmamk_f32 v236, v69, 0x3e38aa3b, v224
	v_fmamk_f32 v237, v70, 0x3e38aa3b, v224
	v_fmamk_f32 v226, v71, 0x3e38aa3b, v224
	v_fmamk_f32 v227, v72, 0x3e38aa3b, v224
	v_fmamk_f32 v228, v73, 0x3e38aa3b, v224
	v_fmamk_f32 v229, v74, 0x3e38aa3b, v224
	v_fmamk_f32 v230, v75, 0x3e38aa3b, v224
	v_fmamk_f32 v231, v76, 0x3e38aa3b, v224
	v_fmamk_f32 v232, v77, 0x3e38aa3b, v224
	v_fmamk_f32 v225, v78, 0x3e38aa3b, v224
	v_fmamk_f32 v238, v79, 0x3e38aa3b, v224
	v_fmamk_f32 v239, v80, 0x3e38aa3b, v224
	v_fmac_f32_e32 v224, 0x3e38aa3b, v81
	s_waitcnt lgkmcnt(0)
	s_barrier
	ds_read_b128 v[66:69], v215 offset:32768
	ds_read_b128 v[70:73], v215 offset:36864
	ds_read_b128 v[182:185], v217 offset:32768
	ds_read_b128 v[190:193], v217 offset:36864
	ds_read_b128 v[168:171], v218 offset:32768
	ds_read_b128 v[194:197], v218 offset:36864
	v_exp_f32_e32 v164, v233
	v_exp_f32_e32 v233, v224
	v_add_f32_e32 v224, 0, v138
	v_add_f32_e32 v224, v153, v224
	s_waitcnt lgkmcnt(5)
	v_mfma_f32_32x32x16_bf16 v[82:97], v[66:69], v[110:113], 0
	v_add_f32_e32 v224, v139, v224
	v_add_f32_e32 v224, v152, v224
	v_add_f32_e32 v224, v140, v224
	ds_read_b128 v[240:243], v216 offset:32768
	ds_read_b128 v[244:247], v216 offset:36864
	v_add_f32_e32 v224, v151, v224
	v_add_f32_e32 v224, v141, v224
	v_add_f32_e32 v224, v150, v224
	s_waitcnt lgkmcnt(6)
	v_mfma_f32_32x32x16_bf16 v[66:81], v[70:73], v[110:113], 0
	v_add_f32_e32 v224, v142, v224
	v_add_f32_e32 v224, v149, v224
	v_add_f32_e32 v224, v143, v224
	v_add_f32_e32 v224, v148, v224
	v_add_f32_e32 v224, v144, v224
	v_exp_f32_e32 v165, v234
	v_add_f32_e32 v224, v147, v224
	s_waitcnt lgkmcnt(1)
	v_mfma_f32_32x32x16_bf16 v[82:97], v[240:243], v[106:109], v[82:97]
	v_exp_f32_e32 v166, v235
	v_add_f32_e32 v224, v145, v224
	v_exp_f32_e32 v167, v236
	v_add_f32_e32 v224, v146, v224
	v_exp_f32_e32 v172, v237
	v_add_f32_e32 v224, v164, v224
	v_exp_f32_e32 v173, v226
	s_waitcnt lgkmcnt(0)
	v_mfma_f32_32x32x16_bf16 v[66:81], v[244:247], v[106:109], v[66:81]
	v_add_f32_e32 v224, v165, v224
	v_exp_f32_e32 v174, v227
	v_add_f32_e32 v224, v166, v224
	v_exp_f32_e32 v175, v228
	v_add_f32_e32 v224, v167, v224
	v_exp_f32_e32 v226, v229
	s_waitcnt lgkmcnt(0)
	v_mfma_f32_32x32x16_bf16 v[82:97], v[182:185], v[102:105], v[82:97]
	v_add_f32_e32 v224, v172, v224
	v_exp_f32_e32 v227, v230
	v_add_f32_e32 v224, v173, v224
	v_exp_f32_e32 v228, v231
	v_add_f32_e32 v224, v174, v224
	v_exp_f32_e32 v229, v232
	v_add_f32_e32 v224, v175, v224
	s_waitcnt lgkmcnt(0)
	v_mfma_f32_32x32x16_bf16 v[66:81], v[190:193], v[102:105], v[66:81]
	v_exp_f32_e32 v230, v225
	v_add_f32_e32 v224, v226, v224
	v_exp_f32_e32 v231, v238
	v_add_f32_e32 v224, v227, v224
	v_exp_f32_e32 v232, v239
	v_add_f32_e32 v224, v228, v224
	s_waitcnt lgkmcnt(0)
	v_mfma_f32_32x32x16_bf16 v[82:97], v[168:171], v[98:101], v[82:97]
	v_add_f32_e32 v224, v229, v224
	v_add_f32_e32 v224, v230, v224
	v_add_f32_e32 v224, v231, v224
	v_add_f32_e32 v224, v232, v224
	v_add_f32_e32 v224, v233, v224
	v_mov_b32_e32 v225, v224
	v_cvt_pk_bf16_f32 v138, v138, v153
	s_waitcnt lgkmcnt(0)
	v_mfma_f32_32x32x16_bf16 v[66:81], v[194:197], v[98:101], v[66:81]
	v_cvt_pk_bf16_f32 v139, v139, v152
	v_cvt_pk_bf16_f32 v140, v140, v151
	v_cvt_pk_bf16_f32 v141, v141, v150
	v_cvt_pk_bf16_f32 v142, v142, v149
	v_cvt_pk_bf16_f32 v143, v143, v148
	v_cvt_pk_bf16_f32 v144, v144, v147
	v_cvt_pk_bf16_f32 v145, v145, v146
	v_cvt_pk_bf16_f32 v146, v164, v165
	v_cvt_pk_bf16_f32 v147, v166, v167
	v_cvt_pk_bf16_f32 v148, v172, v173
	v_cvt_pk_bf16_f32 v149, v174, v175
	v_cvt_pk_bf16_f32 v150, v226, v227
	v_cvt_pk_bf16_f32 v151, v228, v229
	v_cvt_pk_bf16_f32 v152, v230, v231
	v_cvt_pk_bf16_f32 v153, v232, v233
	v_permlane32_swap_b32_e32 v224, v225
	v_permlane32_swap_b32_e32 v138, v140
	v_permlane32_swap_b32_e32 v139, v141
	v_permlane32_swap_b32_e32 v142, v144
	v_permlane32_swap_b32_e32 v143, v145
	v_permlane32_swap_b32_e32 v146, v148
	v_permlane32_swap_b32_e32 v147, v149
	v_permlane32_swap_b32_e32 v150, v152
	v_permlane32_swap_b32_e32 v151, v153
	s_cmp_gt_u32 s8, 60
	s_cselect_b64 s[4:5], -1, 0
	s_and_b64 vcc, exec, s[4:5]
	s_cbranch_vccnz .LBB0_707
	v_add_co_u32_e32 v114, vcc, 0xe180000, v160
	s_nop 1
	v_addc_co_u32_e32 v115, vcc, 0, v161, vcc
	v_add_co_u32_e32 v118, vcc, 0xe1d0000, v160
	s_nop 1
	v_addc_co_u32_e32 v119, vcc, 0, v161, vcc
	v_add_co_u32_e32 v122, vcc, 0xe180000, v176
	global_load_dwordx4 v[114:117], v[114:115], off offset:2048
	s_nop 0
	global_load_dwordx4 v[118:121], v[118:119], off offset:2048
	v_addc_co_u32_e32 v123, vcc, 0, v177, vcc
	global_load_dwordx4 v[122:125], v[122:123], off offset:1152
